# GLA: gq/gk/gkt stored in MFMA-fragment-major order by the prep phase; scan fragment loads now coalesced 1KB reads
# speedup vs baseline: 1.0661x; 1.0235x over previous
; __device__ __forceinline__ int TID() { int t = threadIdx.x; asm volatile("" : "+v"(t)); return t; }
; DI bf16_t f2bf(float x) { return (bf16_t)(pk_bf16(x, 0.f) & 0xffffu); }
; DI void phase_gla_prep(const Params& p, int g, char* smem, int bid, int nb) {
;     ...
;   const int tid = TID(), d = tid & 127, half = tid >> 7;
;   for (int item = bid; item < 2048; item += nb) {
;     const int c = item & 255, head = (item >> 8) & 3, dir = item >> 10, dd = head * 128 + d;
;     ...
;       gq[(blk * 64 + t) * 128 + d] = f2bf(qt);
;       const bf16_t kb = f2bf(kt);
;       gk[(blk * 64 + t) * 128 + d] = kb;
;       if (tt & 1) ktp[tt >> 1] |= ((unsigned)kb) << 16; else ktp[tt >> 1] = kb;
;     }
;     bf16_t* kd = gkt + (blk * 128 + d) * 64 + half * 32;
; #pragma unroll
;     for (int q = 0; q < 4; ++q) { u32x4 v = {ktp[4 * q], ktp[4 * q + 1], ktp[4 * q + 2], ktp[4 * q + 3]}; *(u32x4*)(kd + 8 * q) = v; }
.LBB0_241:
	s_andn2_b64 vcc, exec, s[0:1]
	s_cbranch_vccnz .LBB0_733
	s_cmp_gt_i32 s86, 2
	s_mov_b64 s[0:1], -1
	s_cbranch_scc0 .LBB0_342
	v_readlane_b32 s0, v233, 24
	v_readlane_b32 s1, v233, 25
	v_mov_b32_e32 v8, v195
	s_andn2_b64 vcc, exec, s[0:1]
	s_cbranch_vccnz .LBB0_341
	s_waitcnt vmcnt(0) lgkmcnt(0)
	v_and_b32_e32 v0, 0x7f, v195
	v_lshrrev_b32_e32 v12, 7, v195
	v_lshl_add_u32 v1, v195, 2, 32
	v_lshl_add_u32 v2, v12, 11, 32
	v_lshl_add_u32 v3, v0, 2, 32
	v_lshlrev_b32_e32 v4, 1, v0
	v_mul_u32_u24_e32 v13, 0x50000, v12
	v_add_u32_e32 v4, 0x800, v4
	v_add_u32_e32 v4, v4, v13
	v_and_b32_e32 v5, 7, v0
	v_lshlrev_b32_e32 v5, 1, v5
	v_bfe_u32 v6, v0, 3, 1
	v_lshl_add_u32 v5, v6, 9, v5
	v_lshrrev_b32_e32 v6, 4, v0
	v_lshl_add_u32 v5, v6, 10, v5
	v_lshl_add_u32 v5, v12, 13, v5
	v_lshrrev_b32_e32 v7, 4, v195
	v_and_b32_e32 v13, 15, v195
	v_lshlrev_b32_e32 v13, 2, v13
	v_lshl_add_u32 v7, v7, 7, v13
	v_add_u32_e32 v8, 0x1000, v7
	v_lshlrev_b32_e32 v9, 2, v0
	v_and_b32_e32 v10, 31, v0
	v_lshlrev_b32_e32 v10, 4, v10
	v_lshrrev_b32_e32 v6, 5, v0
	v_lshl_add_u32 v10, v6, 12, v10
	v_lshl_add_u32 v10, v12, 11, v10
	v_readfirstlane_b32 s8, v12
	v_readlane_b32 s12, v235, 0
	s_branch .Lgp_loop

; __device__ __forceinline__ int TID() { int t = threadIdx.x; asm volatile("" : "+v"(t)); return t; }
; DI void gla_scan_unit(const Params& p, int g, int u, char* smem) {
;   const GroupInfo gi = group_info(p, g);
;   bf16_t* St = (bf16_t*)smem;
;   bf16_t* Am = St + 64 * 136;
;   const int slice = u & 3, dir = (u >> 2) & 1, head = (u >> 3) & 3, seq = u >> 5;
;   const int nchunk = gi.S >> 6, chunk0 = seq * nchunk;
;   const int tid = TID(), lane = tid & 63, wave = tid >> 6, wi = wave >> 1, wd = wave & 1, h = lane >> 5, l31 = lane & 31;
;   const bf16_t* gq = (const bf16_t*)(p.ws + OFF_GQ); const bf16_t* gk = (const bf16_t*)(p.ws + OFF_GK); const bf16_t* gkt = (const bf16_t*)(p.ws + OFF_GKT);
;   const float* ge = (const float*)(p.ws + OFF_GE); const bf16_t* vgT = (const bf16_t*)(p.ws + OFF_VGT);
;   bf16_t* od = (bf16_t*)gi.out + (size_t)dir * TOKG * 1024;
;   __syncthreads();
;   for (int i = tid; i < 64 * 136 / 2; i += 256) ((unsigned*)St)[i] = 0u;
;   f32x16 Sacc[2];
; #pragma unroll
;   for (int t = 0; t < 2; ++t)
; #pragma unroll
;     for (int r = 0; r < 16; ++r) Sacc[t][r] = 0.f;
;   __syncthreads();
;   auto blk_of = [&](int step) __attribute__((always_inline)) { return (size_t)((dir * 4 + head) * 256 + chunk0 + (dir ? nchunk - 1 - step : step)); };
;   bf16x8 qf[8], kf[8];
;   {
;     const size_t blk = blk_of(0);
; #pragma unroll
;     for (int s = 0; s < 8; ++s) { qf[s] = *(const bf16x8*)(gq + blk * 8192 + (wi * 32 + l31) * 128 + s * 16 + h * 8); kf[s] = *(const bf16x8*)(gk + blk * 8192 + (wd * 32 + l31) * 128 + s * 16 + h * 8); }
;   }
.LBB0_313:
	s_or_b64 exec, exec, s[0:1]
	v_readlane_b32 s0, v231, 34
	s_add_i32 s0, s12, s0
	s_bfe_u32 s6, s0, 0x10002
	s_ashr_i32 s7, s0, 5
	v_readlane_b32 s8, v231, 35
	v_ashrrev_i32_e32 v1, 7, v0
	v_bfe_u32 v10, v0, 6, 1
	v_bfe_u32 v4, v0, 5, 1
	s_bfe_i32 s1, s0, 0x10002
	s_lshl_b32 s84, s7, s8
	v_and_b32_e32 v12, 31, v0
	s_lshl_b32 s7, s6, 25
	v_readlane_b32 s8, v231, 23
	v_lshlrev_b32_e32 v196, 5, v1
	v_lshlrev_b32_e32 v11, 5, v10
	v_lshlrev_b32_e32 v198, 2, v4
	s_add_u32 s8, s8, s7
	v_readlane_b32 s7, v231, 24
	v_or_b32_e32 v13, v196, v12
	v_or_b32_e32 v14, v11, v198
	s_addc_u32 s9, s7, 0
	v_cmp_le_i32_e32 vcc, v14, v13
	s_cmp_eq_u32 s6, 0
	v_readlane_b32 s39, v231, 36
	v_cndmask_b32_e64 v15, 0, 1, vcc
	v_cmp_ge_i32_e32 vcc, v14, v13
	v_lshlrev_b32_e32 v5, 7, v12
	v_lshlrev_b32_e32 v17, 12, v1
	v_cndmask_b32_e64 v16, 0, 1, vcc
	s_cselect_b64 vcc, -1, 0
	s_lshl_b32 s0, s0, 5
	s_lshl_b32 s6, s6, 10
	s_and_b32 s78, s0, 0x300
	s_or_b32 s79, s6, s78
	s_and_b32 s1, s1, s39
	s_add_i32 s80, s79, s84
	s_add_i32 s0, s80, s1
	s_ashr_i32 s1, s0, 31
	s_lshl_b64 s[0:1], s[0:1], 14
	s_add_u32 s6, s4, s0
	s_addc_u32 s7, s5, s1
	v_lshlrev_b32_e32 v18, 3, v4
	v_lshlrev_b32_e32 v192, 4, v4
	s_add_u32 s0, s68, s0
	v_lshl_or_b32 v4, v10, 12, v5
	v_lshlrev_b32_e32 v2, 3, v12
	v_lshl_or_b32 v2, v198, 6, v2
	v_or_b32_e32 v2, v17, v2
	s_addc_u32 s1, s69, s1
	v_lshlrev_b32_e32 v6, 4, v12
	v_lshl_or_b32 v6, v198, 7, v6
	v_lshl_or_b32 v6, v10, 13, v6
	v_mov_b32_e32 v7, v193
	v_ashrrev_i32_e32 v3, 31, v2
	v_lshl_add_u64 v[8:9], s[0:1], 0, v[6:7]
	s_lshl_b32 s0, s12, 6
	v_lshl_add_u64 v[2:3], v[2:3], 1, s[6:7]
	s_and_b32 s6, s0, 0xc0
	s_lshl_b32 s0, s6, 7
	s_add_u32 s0, s64, s0
	v_mov_b32_e32 v5, v193
	s_addc_u32 s1, s65, 0
	s_waitcnt lgkmcnt(0)
	s_barrier
	v_add_co_u32_e64 v20, s[10:11], s81, v2
	s_nop 1
	v_addc_co_u32_e64 v21, s[10:11], 0, v3, s[10:11]
	v_add_co_u32_e64 v22, s[10:11], s81, v8
	s_nop 1
	v_addc_co_u32_e64 v23, s[10:11], 0, v9, s[10:11]
	global_load_dwordx4 v[76:79], v[2:3], off
	global_load_dwordx4 v[72:75], v[2:3], off offset:1024
	global_load_dwordx4 v[100:103], v[8:9], off
	global_load_dwordx4 v[104:107], v[8:9], off offset:1024
	global_load_dwordx4 v[68:71], v[2:3], off offset:2048
	global_load_dwordx4 v[64:67], v[2:3], off offset:3072
	global_load_dwordx4 v[108:111], v[8:9], off offset:2048
	global_load_dwordx4 v[96:99], v[8:9], off offset:3072
	global_load_dwordx4 v[60:63], v[20:21], off
	global_load_dwordx4 v[56:59], v[20:21], off offset:1024
	global_load_dwordx4 v[92:95], v[22:23], off
	global_load_dwordx4 v[84:87], v[22:23], off offset:1024
	global_load_dwordx4 v[52:55], v[20:21], off offset:2048
	global_load_dwordx4 v[48:51], v[20:21], off offset:3072
	global_load_dwordx4 v[88:91], v[22:23], off offset:2048
	global_load_dwordx4 v[80:83], v[22:23], off offset:3072
	v_lshl_add_u64 v[2:3], s[0:1], 0, v[4:5]
	v_readlane_b32 s0, v233, 20
	v_readlane_b32 s1, v233, 21
	v_lshl_add_u64 v[202:203], s[68:69], 0, v[6:7]
	v_lshl_add_u64 v[200:201], v[2:3], 0, v[192:193]
	v_mov_b32_e32 v2, s0
	v_mov_b32_e32 v3, s1
	v_or_b32_e32 v5, v11, v12
	s_movk_i32 s0, 0x110
	v_mad_u32_u24 v223, v5, s0, 32
	v_readlane_b32 s0, v233, 22
	v_readlane_b32 s1, v233, 23
	s_movk_i32 s10, 0x90
	v_mul_lo_u32 v4, v13, s10
	v_lshl_add_u64 v[8:9], s[0:1], 0, v[192:193]
	s_lshl_b32 s0, s78, 1
	s_add_u32 s0, s8, s0
	v_add_u32_e32 v221, 32, v4
	v_lshlrev_b32_e32 v4, 6, v10
	s_addc_u32 s1, s9, 0
	v_mov_b32_e32 v5, v193
	v_add_u32_e32 v19, v221, v4
	v_lshl_add_u64 v[4:5], s[0:1], 0, v[4:5]
	v_lshlrev_b32_e32 v10, 1, v12
	v_mov_b32_e32 v11, v193
	v_lshl_add_u64 v[4:5], v[4:5], 0, v[10:11]
	s_lshl_b32 s50, s6, 1
	v_lshlrev_b32_e32 v6, 3, v12
	v_lshl_or_b32 v6, v198, 6, v6
	v_or_b32_e32 v6, v17, v6
	v_lshl_add_u64 v[206:207], v[4:5], 0, s[50:51]
	v_cndmask_b32_e32 v5, v16, v15, vcc
	v_ashrrev_i32_e32 v7, 31, v6
	v_and_b32_e32 v5, 1, v5
	v_lshl_add_u64 v[6:7], v[6:7], 1, s[4:5]
	v_cmp_eq_u32_e64 s[0:1], 1, v5
	v_or_b32_e32 v5, 1, v14
	v_cmp_lt_i32_e64 s[6:7], v14, v13
	v_mov_b32_e32 v204, v6
	v_mov_b32_e32 v205, v7
	v_and_b32_e32 v0, 0xffffff80, v0
	v_cndmask_b32_e64 v7, 0, 1, s[6:7]
	v_cmp_ge_i32_e64 s[6:7], v5, v13
	v_add_u32_e32 v4, v223, v0
	v_lshlrev_b32_e32 v0, 3, v12
	v_lshl_or_b32 v0, v198, 6, v0
	v_or_b32_e32 v0, v17, v0
	v_cndmask_b32_e64 v5, 0, 1, s[6:7]
	v_cndmask_b32_e32 v5, v5, v7, vcc
	v_and_b32_e32 v5, 1, v5
	v_cmp_eq_u32_e64 s[36:37], 1, v5
	v_or_b32_e32 v5, 2, v14
	v_cmp_le_i32_e64 s[6:7], v5, v13
	v_lshlrev_b32_e32 v6, 6, v1
	v_ashrrev_i32_e32 v1, 31, v0
	v_cndmask_b32_e64 v7, 0, 1, s[6:7]
	v_cmp_ge_i32_e64 s[6:7], v5, v13
	v_lshl_add_u64 v[238:239], v[0:1], 1, v[2:3]
	v_mov_b32_e32 v0, 0
	v_cndmask_b32_e64 v5, 0, 1, s[6:7]
	v_cndmask_b32_e32 v5, v5, v7, vcc
	v_and_b32_e32 v5, 1, v5
	v_cmp_eq_u32_e64 s[6:7], 1, v5
	v_or_b32_e32 v5, 3, v14
	v_cmp_le_i32_e64 s[8:9], v5, v13
	s_mov_b32 s38, 0
	v_ashrrev_i32_e32 v197, 31, v196
	v_cndmask_b32_e64 v7, 0, 1, s[8:9]
	v_cmp_ge_i32_e64 s[8:9], v5, v13
	v_or_b32_e32 v208, 1, v198
	v_or_b32_e32 v210, 2, v198
	v_cndmask_b32_e64 v5, 0, 1, s[8:9]
	v_cndmask_b32_e32 v5, v5, v7, vcc
	v_and_b32_e32 v5, 1, v5
	v_cmp_eq_u32_e64 s[8:9], 1, v5
	v_or_b32_e32 v5, 8, v14
	v_cmp_le_i32_e64 s[10:11], v5, v13
	v_or_b32_e32 v212, 3, v198
	v_or_b32_e32 v214, 8, v198
	v_cndmask_b32_e64 v7, 0, 1, s[10:11]
	v_cmp_ge_i32_e64 s[10:11], v5, v13
	v_or_b32_e32 v216, 9, v198
	v_or_b32_e32 v218, 10, v198
	v_cndmask_b32_e64 v5, 0, 1, s[10:11]
	v_cndmask_b32_e32 v5, v5, v7, vcc
	v_and_b32_e32 v5, 1, v5
	v_cmp_eq_u32_e64 s[10:11], 1, v5
	v_or_b32_e32 v5, 9, v14
	v_cmp_le_i32_e64 s[12:13], v5, v13
	v_or_b32_e32 v220, 11, v198
	v_or_b32_e32 v222, 16, v198
; #define MFMA32(a, b, c) __builtin_amdgcn_mfma_f32_32x32x16_bf16((a), (b), (c), 0, 0, 0)
; DI void gla_scan_unit(const Params& p, int g, int u, char* smem) {
;     ...
;   f32x16 Sacc[2];
; #pragma unroll
;   for (int t = 0; t < 2; ++t)
; #pragma unroll
;     for (int r = 0; r < 16; ++r) Sacc[t][r] = 0.f;
;     ...
;   for (int step = 0; step < nchunk; ++step) {
;     const int cgk = chunk0 + (dir ? nchunk - 1 - step : step);
;     const size_t blk = (size_t)((dir * 4 + head) * 256 + cgk);
;     const size_t blkn = blk_of(step + 1 < nchunk ? step + 1 : step);
;     const bf16_t* gkt_c = gkt + blk * 8192;
;     const bf16_t* vt_c = vgT + ((size_t)(head * 256 + cgk) * 256 + slice * 64) * 64;
;     const float* e_c = ge + blk * 128;
;     bf16x8 vf[4], ktf[2][4]; f32x4 ev[2][4];
; #pragma unroll
;     for (int s = 0; s < 4; ++s) vf[s] = *(const bf16x8*)(vt_c + (wd * 32 + l31) * 64 + s * 16 + h * 8);
; #pragma unroll
;     for (int t = 0; t < 2; ++t)
; #pragma unroll
;       for (int s = 0; s < 4; ++s) ktf[t][s] = *(const bf16x8*)(gkt_c + ((2 * wi + t) * 32 + l31) * 64 + s * 16 + h * 8);
;     f32x16 X;
; #pragma unroll
;     for (int r = 0; r < 16; ++r) X[r] = 0.f;
; #pragma unroll
;     for (int s = 0; s < 8; ++s) X = MFMA32(kf[s], qf[s], X);
;     __builtin_amdgcn_sched_barrier(0);
; #pragma unroll
;     for (int s = 0; s < 8; ++s) kf[s] = *(const bf16x8*)(gk + blkn * 8192 + (wd * 32 + l31) * 128 + s * 16 + h * 8);
;     {
;       const int gi_ = wi * 32 + l31;
; #pragma unroll
;       for (int q4 = 0; q4 < 4; ++q4) {
;         float v[4];
; #pragma unroll
;         for (int e = 0; e < 4; ++e) { const int gj = wd * 32 + 8 * q4 + 4 * h + e; const bool keep = dir ? (gj >= gi_) : (gj <= gi_); v[e] = keep ? X[4 * q4 + e] : 0.f; }
	v_cndmask_b32_e64 v7, 0, 1, s[12:13]
	v_cmp_ge_i32_e64 s[12:13], v5, v13
	v_or_b32_e32 v224, 17, v198
	v_or_b32_e32 v226, 18, v198
	v_cndmask_b32_e64 v5, 0, 1, s[12:13]
	v_cndmask_b32_e32 v5, v5, v7, vcc
	v_and_b32_e32 v5, 1, v5
	v_cmp_eq_u32_e64 s[12:13], 1, v5
	v_or_b32_e32 v5, 10, v14
	v_cmp_le_i32_e64 s[14:15], v5, v13
	v_or_b32_e32 v228, 19, v198
	v_or_b32_e32 v230, 24, v198
	v_cndmask_b32_e64 v7, 0, 1, s[14:15]
	v_cmp_ge_i32_e64 s[14:15], v5, v13
	v_or_b32_e32 v232, 25, v198
	v_or_b32_e32 v234, 26, v198
	v_cndmask_b32_e64 v5, 0, 1, s[14:15]
	v_cndmask_b32_e32 v5, v5, v7, vcc
	v_and_b32_e32 v5, 1, v5
	v_cmp_eq_u32_e64 s[14:15], 1, v5
	v_or_b32_e32 v5, 11, v14
	v_cmp_le_i32_e64 s[16:17], v5, v13
	v_or_b32_e32 v236, 27, v198
	v_add_u32_e32 v225, v19, v18
	v_cndmask_b32_e64 v7, 0, 1, s[16:17]
	v_cmp_ge_i32_e64 s[16:17], v5, v13
	v_add_u32_e32 v227, v4, v18
	s_mov_b32 s50, s39
	v_cndmask_b32_e64 v5, 0, 1, s[16:17]
	v_cndmask_b32_e32 v5, v5, v7, vcc
	v_and_b32_e32 v5, 1, v5
	v_cmp_eq_u32_e64 s[16:17], 1, v5
	v_or_b32_e32 v5, 16, v14
	v_cmp_le_i32_e64 s[18:19], v5, v13
	v_mov_b32_e32 v1, v0
	v_mov_b32_e32 v2, v0
	v_cndmask_b32_e64 v7, 0, 1, s[18:19]
	v_cmp_ge_i32_e64 s[18:19], v5, v13
	v_mov_b32_e32 v3, v0
	v_mov_b32_e32 v4, v0
	v_cndmask_b32_e64 v5, 0, 1, s[18:19]
	v_cndmask_b32_e32 v5, v5, v7, vcc
	v_and_b32_e32 v5, 1, v5
	v_cmp_eq_u32_e64 s[18:19], 1, v5
	v_or_b32_e32 v5, 17, v14
	v_cmp_le_i32_e64 s[20:21], v5, v13
	v_mov_b32_e32 v10, v0
	v_mov_b32_e32 v11, v0
	v_cndmask_b32_e64 v7, 0, 1, s[20:21]
	v_cmp_ge_i32_e64 s[20:21], v5, v13
	v_mov_b32_e32 v12, v0
	v_mov_b32_e32 v15, v0
	v_cndmask_b32_e64 v5, 0, 1, s[20:21]
	v_cndmask_b32_e32 v5, v5, v7, vcc
	v_and_b32_e32 v5, 1, v5
	v_cmp_eq_u32_e64 s[20:21], 1, v5
	v_or_b32_e32 v5, 18, v14
	v_cmp_le_i32_e64 s[22:23], v5, v13
	v_mov_b32_e32 v16, v0
	v_mov_b32_e32 v17, v0
	v_cndmask_b32_e64 v7, 0, 1, s[22:23]
	v_cmp_ge_i32_e64 s[22:23], v5, v13
	v_mov_b32_e32 v18, v0
	v_mov_b32_e32 v19, v0
	v_cndmask_b32_e64 v5, 0, 1, s[22:23]
	v_cndmask_b32_e32 v5, v5, v7, vcc
	v_and_b32_e32 v5, 1, v5
	v_cmp_eq_u32_e64 s[22:23], 1, v5
	v_or_b32_e32 v5, 19, v14
	v_cmp_le_i32_e64 s[24:25], v5, v13
	v_mov_b32_e32 v20, v0
	v_mov_b32_e32 v21, v0
	v_cndmask_b32_e64 v7, 0, 1, s[24:25]
	v_cmp_ge_i32_e64 s[24:25], v5, v13
	v_mov_b32_e32 v22, v0
	v_mov_b32_e32 v23, v0
	v_cndmask_b32_e64 v5, 0, 1, s[24:25]
	v_cndmask_b32_e32 v5, v5, v7, vcc
	v_and_b32_e32 v5, 1, v5
	v_cmp_eq_u32_e64 s[24:25], 1, v5
	v_or_b32_e32 v5, 24, v14
	v_cmp_le_i32_e64 s[26:27], v5, v13
	v_mov_b32_e32 v24, v0
	v_mov_b32_e32 v25, v0
	v_cndmask_b32_e64 v7, 0, 1, s[26:27]
	v_cmp_ge_i32_e64 s[26:27], v5, v13
	v_mov_b32_e32 v26, v0
	v_mov_b32_e32 v27, v0
	v_cndmask_b32_e64 v5, 0, 1, s[26:27]
	v_cndmask_b32_e32 v5, v5, v7, vcc
	v_and_b32_e32 v5, 1, v5
	v_cmp_eq_u32_e64 s[26:27], 1, v5
	v_or_b32_e32 v5, 25, v14
	v_cmp_le_i32_e64 s[28:29], v5, v13
	v_mov_b32_e32 v28, v0
	v_mov_b32_e32 v29, v0
	v_cndmask_b32_e64 v7, 0, 1, s[28:29]
	v_cmp_ge_i32_e64 s[28:29], v5, v13
	v_mov_b32_e32 v30, v0
	v_mov_b32_e32 v31, v0
	v_cndmask_b32_e64 v5, 0, 1, s[28:29]
	v_cndmask_b32_e32 v5, v5, v7, vcc
	v_and_b32_e32 v5, 1, v5
	v_cmp_eq_u32_e64 s[28:29], 1, v5
	v_or_b32_e32 v5, 26, v14
	v_cmp_le_i32_e64 s[30:31], v5, v13
	s_nop 1
	v_cndmask_b32_e64 v7, 0, 1, s[30:31]
	v_cmp_ge_i32_e64 s[30:31], v5, v13
	s_nop 1
	v_cndmask_b32_e64 v5, 0, 1, s[30:31]
	v_cndmask_b32_e32 v5, v5, v7, vcc
	v_and_b32_e32 v5, 1, v5
	v_cmp_eq_u32_e64 s[30:31], 1, v5
	v_or_b32_e32 v5, 27, v14
	v_cmp_le_i32_e64 s[34:35], v5, v13
	v_mov_b32_e32 v14, v0
	s_nop 0
	v_cndmask_b32_e64 v7, 0, 1, s[34:35]
	v_cmp_ge_i32_e64 s[34:35], v5, v13
	v_mov_b32_e32 v13, v0
	s_nop 0
	v_cndmask_b32_e64 v5, 0, 1, s[34:35]
	v_cndmask_b32_e32 v5, v5, v7, vcc
	v_and_b32_e32 v5, 1, v5
	v_ashrrev_i32_e32 v7, 31, v6
	v_cmp_eq_u32_e64 s[34:35], 1, v5
	v_lshl_add_u64 v[240:241], v[6:7], 2, v[8:9]
	v_mov_b32_e32 v5, v0
	v_mov_b32_e32 v6, v0
	v_mov_b32_e32 v7, v0
	v_mov_b32_e32 v8, v0
	v_mov_b32_e32 v9, v0
	s_waitcnt vmcnt(0)
.LBB0_314:
	s_waitcnt vmcnt(23)
	v_mfma_f32_32x32x16_bf16 v[32:47], v[100:103], v[76:79], 0
	s_and_b64 s[62:63], vcc, exec
	s_cselect_b32 s39, s38, s50
	s_add_i32 s70, s39, s84
	s_add_i32 s62, s70, s79
	s_add_i32 s82, s38, 1
	s_cmp_lt_u32 s82, s73
	s_cselect_b32 s63, s82, s38
	s_waitcnt vmcnt(22)
	v_mfma_f32_32x32x16_bf16 v[32:47], v[104:107], v[72:75], v[32:47]
	s_not_b32 s38, s63
	s_add_i32 s71, s73, s38
	s_and_b64 s[38:39], vcc, exec
	s_cselect_b32 s71, s63, s71
	s_add_i32 s38, s70, s78
	s_ashr_i32 s39, s38, 31
	s_lshl_b64 s[38:39], s[38:39], 15
	s_waitcnt vmcnt(21)
	v_mfma_f32_32x32x16_bf16 v[32:47], v[108:111], v[68:71], v[32:47]
	s_ashr_i32 s63, s62, 31
	s_waitcnt vmcnt(20)
	v_mfma_f32_32x32x16_bf16 v[32:47], v[96:99], v[64:67], v[32:47]
	v_lshl_add_u64 v[96:97], v[200:201], 0, s[38:39]
	s_lshl_b64 s[38:39], s[62:63], 14
	global_load_dwordx4 v[136:139], v[96:97], off
	global_load_dwordx4 v[128:131], v[96:97], off offset:32
	s_waitcnt vmcnt(21)
	v_mfma_f32_32x32x16_bf16 v[32:47], v[92:95], v[60:63], v[32:47]
	v_lshl_add_u64 v[92:93], v[238:239], 0, s[38:39]
	s_lshl_b64 s[38:39], s[62:63], 9
	v_lshl_add_u64 v[144:145], v[240:241], 0, s[38:39]
	global_load_dwordx4 v[188:191], v[144:145], off
	global_load_dwordx4 v[184:187], v[144:145], off offset:32
	global_load_dwordx4 v[180:183], v[144:145], off offset:64
	global_load_dwordx4 v[176:179], v[144:145], off offset:96
	global_load_dwordx4 v[156:159], v[144:145], off offset:128
	global_load_dwordx4 v[152:155], v[144:145], off offset:160
	global_load_dwordx4 v[148:151], v[144:145], off offset:192
	s_nop 0
	global_load_dwordx4 v[144:147], v[144:145], off offset:224
	global_load_dwordx4 v[172:175], v[92:93], off
	global_load_dwordx4 v[168:171], v[92:93], off offset:1024
	global_load_dwordx4 v[120:123], v[96:97], off offset:64
	global_load_dwordx4 v[112:115], v[96:97], off offset:96
	global_load_dwordx4 v[164:167], v[92:93], off offset:2048
	global_load_dwordx4 v[160:163], v[92:93], off offset:3072
	s_waitcnt vmcnt(34)
; #define MFMA32(a, b, c) __builtin_amdgcn_mfma_f32_32x32x16_bf16((a), (b), (c), 0, 0, 0)
; DI unsigned pk_bf16(float lo, float hi) { f32x2 v = {lo, hi}; bf16v2 b = __builtin_convertvector(v, bf16v2); return __builtin_bit_cast(unsigned, b); }
; DI void gla_scan_unit(const Params& p, int g, int u, char* smem) {
;     ...
;     for (int s = 0; s < 8; ++s) X = MFMA32(kf[s], qf[s], X);
;     __builtin_amdgcn_sched_barrier(0);
; #pragma unroll
;     for (int s = 0; s < 8; ++s) kf[s] = *(const bf16x8*)(gk + blkn * 8192 + (wd * 32 + l31) * 128 + s * 16 + h * 8);
;     {
;       const int gi_ = wi * 32 + l31;
; #pragma unroll
;       for (int q4 = 0; q4 < 4; ++q4) {
;         float v[4];
; #pragma unroll
;         for (int e = 0; e < 4; ++e) { const int gj = wd * 32 + 8 * q4 + 4 * h + e; const bool keep = dir ? (gj >= gi_) : (gj <= gi_); v[e] = keep ? X[4 * q4 + e] : 0.f; }
;         u32x2 o; o.x = pk_bf16(v[0], v[1]); o.y = pk_bf16(v[2], v[3]);
;         *(u32x2*)(Am + gi_ * 72 + wd * 32 + 8 * q4 + 4 * h) = o;
;       }
;     }
;     f32x16 o;
; #pragma unroll
;     for (int r = 0; r < 16; ++r) o[r] = 0.f;
; #pragma unroll
;     for (int s = 0; s < 8; ++s) { const bf16x8 sf = *(const bf16x8*)(St + (wd * 32 + l31) * 136 + s * 16 + h * 8); o = MFMA32(qf[s], sf, o); }
;     __builtin_amdgcn_sched_barrier(0);
; #pragma unroll
;     for (int s = 0; s < 8; ++s) qf[s] = *(const bf16x8*)(gq + blkn * 8192 + (wi * 32 + l31) * 128 + s * 16 + h * 8);
	v_mfma_f32_32x32x16_bf16 v[32:47], v[84:87], v[56:59], v[32:47]
	v_add_co_u32_e64 v84, s[38:39], s81, v92
	s_nop 1
	v_addc_co_u32_e64 v85, s[38:39], 0, v93, s[38:39]
	global_load_dwordx4 v[140:143], v[84:85], off
	global_load_dwordx4 v[132:135], v[84:85], off offset:1024
	global_load_dwordx4 v[124:127], v[84:85], off offset:2048
	global_load_dwordx4 v[116:119], v[84:85], off offset:3072
	s_waitcnt vmcnt(36)
	v_mfma_f32_32x32x16_bf16 v[32:47], v[88:91], v[52:55], v[32:47]
	s_add_i32 s38, s71, s80
	s_ashr_i32 s39, s38, 31
	s_waitcnt vmcnt(36)
	v_mfma_f32_32x32x16_bf16 v[32:47], v[80:83], v[48:51], v[32:47]
	s_nop 11
	v_cndmask_b32_e64 v32, 0, v32, s[0:1]
	v_cndmask_b32_e64 v33, 0, v33, s[36:37]
	v_cndmask_b32_e64 v34, 0, v34, s[6:7]
	v_cndmask_b32_e64 v35, 0, v35, s[8:9]
	v_cvt_pk_bf16_f32 v32, v32, v33
	v_cvt_pk_bf16_f32 v33, v34, v35
	v_cndmask_b32_e64 v34, 0, v36, s[10:11]
	v_cndmask_b32_e64 v35, 0, v37, s[12:13]
	v_cndmask_b32_e64 v36, 0, v38, s[14:15]
	v_cndmask_b32_e64 v37, 0, v39, s[16:17]
	v_cvt_pk_bf16_f32 v34, v34, v35
	v_cvt_pk_bf16_f32 v35, v36, v37
	v_add_u32_e32 v36, 0x4000, v225
	ds_write2_b64 v36, v[32:33], v[34:35] offset0:128 offset1:130
	v_cndmask_b32_e64 v32, 0, v40, s[18:19]
	v_cndmask_b32_e64 v33, 0, v41, s[20:21]
	v_cndmask_b32_e64 v34, 0, v42, s[22:23]
	v_cndmask_b32_e64 v35, 0, v43, s[24:25]
	v_cvt_pk_bf16_f32 v32, v32, v33
	v_cvt_pk_bf16_f32 v33, v34, v35
	v_cndmask_b32_e64 v34, 0, v44, s[26:27]
	v_cndmask_b32_e64 v35, 0, v45, s[28:29]
	v_cndmask_b32_e64 v37, 0, v46, s[30:31]
	v_cndmask_b32_e64 v38, 0, v47, s[34:35]
	v_cvt_pk_bf16_f32 v34, v34, v35
	v_cvt_pk_bf16_f32 v35, v37, v38
	ds_write2_b64 v36, v[32:33], v[34:35] offset0:132 offset1:134
	v_add_u32_e32 v88, v223, v192
	ds_read_b128 v[32:35], v88
	ds_read_b128 v[80:83], v88 offset:32
	s_waitcnt lgkmcnt(1)
	v_mfma_f32_32x32x16_bf16 v[32:47], v[76:79], v[32:35], 0
	s_lshl_b64 s[38:39], s[38:39], 14
	s_waitcnt lgkmcnt(0)
	v_mfma_f32_32x32x16_bf16 v[32:47], v[72:75], v[80:83], v[32:47]
	ds_read_b128 v[72:75], v88 offset:64
	ds_read_b128 v[76:79], v88 offset:96
	s_waitcnt lgkmcnt(1)
	v_mfma_f32_32x32x16_bf16 v[32:47], v[68:71], v[72:75], v[32:47]
	s_waitcnt lgkmcnt(0)
	v_mfma_f32_32x32x16_bf16 v[32:47], v[64:67], v[76:79], v[32:47]
	ds_read_b128 v[64:67], v88 offset:128
	ds_read_b128 v[68:71], v88 offset:160
	s_waitcnt lgkmcnt(1)
	v_mfma_f32_32x32x16_bf16 v[32:47], v[60:63], v[64:67], v[32:47]
	v_lshl_add_u64 v[64:65], v[202:203], 0, s[38:39]
	s_mov_b64 s[62:63], 0x1000
	v_lshl_add_u64 v[80:81], v[64:65], 0, s[62:63]
	global_load_dwordx4 v[100:103], v[64:65], off
	global_load_dwordx4 v[104:107], v[64:65], off offset:1024
	s_waitcnt lgkmcnt(0)
	v_mfma_f32_32x32x16_bf16 v[32:47], v[56:59], v[68:71], v[32:47]
	ds_read_b128 v[56:59], v88 offset:192
	global_load_dwordx4 v[108:111], v[64:65], off offset:2048
	global_load_dwordx4 v[96:99], v[64:65], off offset:3072
	global_load_dwordx4 v[92:95], v[80:81], off
	global_load_dwordx4 v[84:87], v[80:81], off offset:1024
	ds_read_b128 v[60:63], v88 offset:224
	global_load_dwordx4 v[88:91], v[80:81], off offset:2048
	s_nop 0
	global_load_dwordx4 v[80:83], v[80:81], off offset:3072
	s_waitcnt lgkmcnt(1)
	v_mfma_f32_32x32x16_bf16 v[32:47], v[52:55], v[56:59], v[32:47]
	s_waitcnt lgkmcnt(0)
	v_mfma_f32_32x32x16_bf16 v[32:47], v[48:51], v[60:63], v[32:47]
	v_lshl_add_u64 v[48:49], v[204:205], 0, s[38:39]
	v_lshl_add_u64 v[52:53], v[48:49], 0, s[62:63]
	global_load_dwordx4 v[76:79], v[48:49], off
	global_load_dwordx4 v[72:75], v[48:49], off offset:1024
	global_load_dwordx4 v[68:71], v[48:49], off offset:2048
	global_load_dwordx4 v[64:67], v[48:49], off offset:3072
	global_load_dwordx4 v[60:63], v[52:53], off
	global_load_dwordx4 v[56:59], v[52:53], off offset:1024
	global_load_dwordx4 v[48:51], v[52:53], off offset:3072
	s_nop 0
	global_load_dwordx4 v[52:55], v[52:53], off offset:2048
	s_waitcnt lgkmcnt(0)
	s_barrier
; #define MFMA32(a, b, c) __builtin_amdgcn_mfma_f32_32x32x16_bf16((a), (b), (c), 0, 0, 0)
; DI void lds_barrier() { asm volatile("s_waitcnt lgkmcnt(0)\n\ts_barrier" ::: "memory"); }
; DI unsigned pk_bf16(float lo, float hi) { f32x2 v = {lo, hi}; bf16v2 b = __builtin_convertvector(v, bf16v2); return __builtin_bit_cast(unsigned, b); }
; DI bf16_t f2bf(float x) { return (bf16_t)(pk_bf16(x, 0.f) & 0xffffu); }
; DI int crow(int r, int h) { return (r & 3) + 8 * (r >> 2) + 4 * h; }
; DI void gla_scan_unit(const Params& p, int g, int u, char* smem) {
;     ...
;     lds_barrier();
; #pragma unroll
;     for (int t = 0; t < 2; ++t)
; #pragma unroll
;       for (int q4 = 0; q4 < 4; ++q4) ev[t][q4] = *(const f32x4*)(e_c + (2 * wi + t) * 32 + 8 * q4 + 4 * h);
; #pragma unroll
;     for (int s = 0; s < 4; ++s) { const bf16x8 af = *(const bf16x8*)(Am + (wi * 32 + l31) * 72 + s * 16 + h * 8); o = MFMA32(af, vf[s], o); }
;     {
;       const size_t tokb = (size_t)cgk * 64 + wi * 32;
; #pragma unroll
;       for (int r = 0; r < 16; ++r) od[(tokb + crow(r, h)) * 1024 + head * 256 + slice * 64 + wd * 32 + l31] = f2bf(o[r]);
;     }
; #pragma unroll
;     for (int t = 0; t < 2; ++t) {
; #pragma unroll
;       for (int s = 0; s < 4; ++s) Sacc[t] = MFMA32(ktf[t][s], vf[s], Sacc[t]);
; #pragma unroll
;       for (int q4 = 0; q4 < 4; ++q4)
; #pragma unroll
;         for (int e = 0; e < 4; ++e) Sacc[t][4 * q4 + e] *= ev[t][q4][e];
;     }
;     lds_barrier();
; #pragma unroll
;     for (int t = 0; t < 2; ++t) {
;       const int dkb = 2 * wi + t;
; #pragma unroll
;       for (int q4 = 0; q4 < 4; ++q4) {
;         u32x2 w; w.x = pk_bf16(Sacc[t][4 * q4], Sacc[t][4 * q4 + 1]); w.y = pk_bf16(Sacc[t][4 * q4 + 2], Sacc[t][4 * q4 + 3]);
;         *(u32x2*)(St + (wd * 32 + l31) * 136 + dkb * 32 + 8 * q4 + 4 * h) = w;
;       }
;     }
;     lds_barrier();
	v_add_u32_e32 v229, v221, v192
	ds_read_b128 v[242:245], v229 offset:17408
	ds_read_b128 v[246:249], v229 offset:17440
	s_waitcnt vmcnt(35) lgkmcnt(1)
	v_mfma_f32_32x32x16_bf16 v[32:47], v[242:245], v[136:139], v[32:47]
	ds_read_b128 v[242:245], v229 offset:17472
	s_ashr_i32 s71, s70, 31
	s_lshl_b64 s[38:39], s[70:71], 6
	s_add_i32 s50, s50, -1
	s_cmp_eq_u32 s82, s73
	s_waitcnt vmcnt(34) lgkmcnt(1)
	v_mfma_f32_32x32x16_bf16 v[32:47], v[246:249], v[128:131], v[32:47]
	s_waitcnt vmcnt(23) lgkmcnt(0)
	v_mfma_f32_32x32x16_bf16 v[32:47], v[242:245], v[120:123], v[32:47]
	ds_read_b128 v[242:245], v229 offset:17504
	s_waitcnt vmcnt(22) lgkmcnt(0)
	v_mfma_f32_32x32x16_bf16 v[32:47], v[242:245], v[112:115], v[32:47]
	v_lshl_add_u64 v[242:243], s[38:39], 0, v[196:197]
	v_or_b32_e32 v244, v242, v198
	v_mov_b32_e32 v245, v243
	v_lshlrev_b64 v[244:245], 11, v[244:245]
	v_lshl_add_u64 v[244:245], v[206:207], 0, v[244:245]
	s_mov_b32 s38, s82
	s_nop 5
	v_cvt_pk_bf16_f32 v32, v32, s0
	global_store_short v[244:245], v32, off
	v_cvt_pk_bf16_f32 v229, v33, s0
	v_or_b32_e32 v32, v242, v208
	v_mov_b32_e32 v33, v243
	v_lshlrev_b64 v[32:33], 11, v[32:33]
	v_lshl_add_u64 v[32:33], v[206:207], 0, v[32:33]
	global_store_short v[32:33], v229, off
	v_or_b32_e32 v32, v242, v210
	v_mov_b32_e32 v33, v243
	v_lshlrev_b64 v[32:33], 11, v[32:33]
	v_cvt_pk_bf16_f32 v34, v34, s0
	v_lshl_add_u64 v[32:33], v[206:207], 0, v[32:33]
	global_store_short v[32:33], v34, off
	v_or_b32_e32 v32, v242, v212
	v_mov_b32_e32 v33, v243
	v_lshlrev_b64 v[32:33], 11, v[32:33]
	v_cvt_pk_bf16_f32 v34, v35, s0
	v_lshl_add_u64 v[32:33], v[206:207], 0, v[32:33]
	global_store_short v[32:33], v34, off
	v_or_b32_e32 v32, v242, v214
	v_mov_b32_e32 v33, v243
	v_lshlrev_b64 v[32:33], 11, v[32:33]
	v_cvt_pk_bf16_f32 v34, v36, s0
	v_lshl_add_u64 v[32:33], v[206:207], 0, v[32:33]
	v_mfma_f32_32x32x16_bf16 v[0:15], v[172:175], v[136:139], v[0:15]
	global_store_short v[32:33], v34, off
	v_or_b32_e32 v32, v242, v216
	v_mov_b32_e32 v33, v243
	v_lshlrev_b64 v[32:33], 11, v[32:33]
	v_cvt_pk_bf16_f32 v34, v37, s0
	v_lshl_add_u64 v[32:33], v[206:207], 0, v[32:33]
	global_store_short v[32:33], v34, off
	s_waitcnt vmcnt(25)
	v_mfma_f32_32x32x16_bf16 v[16:31], v[140:143], v[136:139], v[16:31]
	v_or_b32_e32 v32, v242, v218
	v_mov_b32_e32 v33, v243
	v_lshlrev_b64 v[32:33], 11, v[32:33]
	v_cvt_pk_bf16_f32 v34, v38, s0
	v_lshl_add_u64 v[32:33], v[206:207], 0, v[32:33]
	global_store_short v[32:33], v34, off
	v_or_b32_e32 v32, v242, v220
	v_mov_b32_e32 v33, v243
	v_lshlrev_b64 v[32:33], 11, v[32:33]
	v_mfma_f32_32x32x16_bf16 v[0:15], v[168:171], v[128:131], v[0:15]
	v_cvt_pk_bf16_f32 v34, v39, s0
	v_lshl_add_u64 v[32:33], v[206:207], 0, v[32:33]
	global_store_short v[32:33], v34, off
	v_or_b32_e32 v32, v242, v222
	v_mov_b32_e32 v33, v243
	v_lshlrev_b64 v[32:33], 11, v[32:33]
	v_cvt_pk_bf16_f32 v34, v40, s0
	s_waitcnt vmcnt(26)
	v_mfma_f32_32x32x16_bf16 v[16:31], v[132:135], v[128:131], v[16:31]
	v_lshl_add_u64 v[32:33], v[206:207], 0, v[32:33]
	global_store_short v[32:33], v34, off
	v_or_b32_e32 v32, v242, v224
	v_mov_b32_e32 v33, v243
	v_lshlrev_b64 v[32:33], 11, v[32:33]
	v_cvt_pk_bf16_f32 v34, v41, s0
	v_lshl_add_u64 v[32:33], v[206:207], 0, v[32:33]
	global_store_short v[32:33], v34, off
	v_or_b32_e32 v32, v242, v226
	v_mov_b32_e32 v33, v243
	v_mfma_f32_32x32x16_bf16 v[0:15], v[164:167], v[120:123], v[0:15]
	v_lshlrev_b64 v[32:33], 11, v[32:33]
	v_cvt_pk_bf16_f32 v34, v42, s0
	v_lshl_add_u64 v[32:33], v[206:207], 0, v[32:33]
	global_store_short v[32:33], v34, off
	v_or_b32_e32 v32, v242, v228
	v_mov_b32_e32 v33, v243
	v_lshlrev_b64 v[32:33], 11, v[32:33]
	s_waitcnt vmcnt(28)
	v_mfma_f32_32x32x16_bf16 v[16:31], v[124:127], v[120:123], v[16:31]
	v_cvt_pk_bf16_f32 v34, v43, s0
	v_lshl_add_u64 v[32:33], v[206:207], 0, v[32:33]
	global_store_short v[32:33], v34, off
	v_or_b32_e32 v32, v242, v230
	v_mov_b32_e32 v33, v243
	v_lshlrev_b64 v[32:33], 11, v[32:33]
	v_cvt_pk_bf16_f32 v34, v44, s0
	v_lshl_add_u64 v[32:33], v[206:207], 0, v[32:33]
	v_mfma_f32_32x32x16_bf16 v[0:15], v[160:163], v[112:115], v[0:15]
	global_store_short v[32:33], v34, off
	v_or_b32_e32 v32, v242, v232
	v_mov_b32_e32 v33, v243
	v_lshlrev_b64 v[32:33], 11, v[32:33]
	v_cvt_pk_bf16_f32 v34, v45, s0
	v_lshl_add_u64 v[32:33], v[206:207], 0, v[32:33]
	global_store_short v[32:33], v34, off
	s_waitcnt vmcnt(30)
	v_mfma_f32_32x32x16_bf16 v[16:31], v[116:119], v[112:115], v[16:31]
	v_or_b32_e32 v32, v242, v234
	v_mov_b32_e32 v33, v243
	v_lshlrev_b64 v[32:33], 11, v[32:33]
	v_cvt_pk_bf16_f32 v34, v46, s0
	v_lshl_add_u64 v[32:33], v[206:207], 0, v[32:33]
	v_or_b32_e32 v242, v242, v236
	global_store_short v[32:33], v34, off
	v_lshlrev_b64 v[32:33], 11, v[242:243]
	v_cvt_pk_bf16_f32 v34, v47, s0
	v_lshl_add_u64 v[32:33], v[206:207], 0, v[32:33]
	v_pk_mul_f32 v[0:1], v[188:189], v[0:1]
	v_pk_mul_f32 v[2:3], v[190:191], v[2:3]
	v_pk_mul_f32 v[4:5], v[184:185], v[4:5]
	v_pk_mul_f32 v[6:7], v[186:187], v[6:7]
	global_store_short v[32:33], v34, off
	v_pk_mul_f32 v[8:9], v[180:181], v[8:9]
	v_pk_mul_f32 v[10:11], v[182:183], v[10:11]
	v_pk_mul_f32 v[12:13], v[176:177], v[12:13]
	v_pk_mul_f32 v[14:15], v[178:179], v[14:15]
	v_cvt_pk_bf16_f32 v32, v0, v1
	v_cvt_pk_bf16_f32 v33, v2, v3
	v_cvt_pk_bf16_f32 v34, v4, v5
	v_cvt_pk_bf16_f32 v35, v6, v7
	v_pk_mul_f32 v[16:17], v[156:157], v[16:17]
	v_pk_mul_f32 v[18:19], v[158:159], v[18:19]
	v_pk_mul_f32 v[20:21], v[152:153], v[20:21]
	v_pk_mul_f32 v[22:23], v[154:155], v[22:23]
	s_waitcnt lgkmcnt(0)
	s_barrier
	ds_write2_b64 v227, v[32:33], v[34:35] offset1:2
	v_cvt_pk_bf16_f32 v32, v8, v9
	v_cvt_pk_bf16_f32 v33, v10, v11
	v_cvt_pk_bf16_f32 v34, v12, v13
	v_cvt_pk_bf16_f32 v35, v14, v15
	v_pk_mul_f32 v[24:25], v[148:149], v[24:25]
	v_pk_mul_f32 v[26:27], v[150:151], v[26:27]
	v_pk_mul_f32 v[28:29], v[144:145], v[28:29]
	v_pk_mul_f32 v[30:31], v[146:147], v[30:31]
	ds_write2_b64 v227, v[32:33], v[34:35] offset0:4 offset1:6
	v_cvt_pk_bf16_f32 v32, v16, v17
	v_cvt_pk_bf16_f32 v33, v18, v19
	v_cvt_pk_bf16_f32 v34, v20, v21
	v_cvt_pk_bf16_f32 v35, v22, v23
	ds_write2_b64 v227, v[32:33], v[34:35] offset0:8 offset1:10
	v_cvt_pk_bf16_f32 v32, v24, v25
	v_cvt_pk_bf16_f32 v33, v26, v27
	v_cvt_pk_bf16_f32 v34, v28, v29
	v_cvt_pk_bf16_f32 v35, v30, v31
	ds_write2_b64 v227, v[32:33], v[34:35] offset0:12 offset1:14
	s_waitcnt lgkmcnt(0)
	s_barrier
	s_cbranch_scc0 .LBB0_314
	s_branch .LBB0_245

; DI float bf2f(bf16_t v) { return __uint_as_float(((unsigned)v) << 16); }
; DI void phase_gla_prep(const Params& p, int g, char* smem, int bid, int nb) {
;     ...
;   for (int item = bid; item < 2048; item += nb) {
;     const int c = item & 255, head = (item >> 8) & 3, dir = item >> 10, dd = head * 128 + d;
;     __syncthreads();
; #pragma unroll
;     for (int i = 0; i < 4; ++i) { const int idx = tid + 256 * i; lrs[idx] = lrb[(size_t)(c * 64 + (idx >> 4)) * 32 + dir * 16 + (idx & 15)]; }
;     const float* wgp = dir ? p.w_gate_b : p.w_gate_f;
;     float wg[16];
; #pragma unroll
;     for (int r = 0; r < 16; ++r) wg[r] = wgp[r * 512 + dd];
;     const float bg = (dir ? p.b_gate_b : p.b_gate_f)[dd];
;     __syncthreads();
;     ...
;       const float qv = bf2f(proj[tg * NPROJ + PQG + dd]), kv = bf2f(proj[tg * NPROJ + PKG + dd]);
.Lgp_loop:
	s_and_b32 s10, s12, 0xff
	s_bfe_u32 s11, s12, 0x20008
	s_lshr_b32 s13, s12, 10
	s_lshl_b32 s0, s13, 2
	s_add_i32 s0, s0, s11
	s_lshl_b32 s0, s0, 8
	s_add_i32 s9, s0, s10
	v_readlane_b32 s16, v233, 26
	v_readlane_b32 s17, v233, 27
	s_lshl_b32 s0, s10, 13
	s_lshl_b32 s1, s13, 6
	s_add_i32 s0, s0, s1
	s_nop 1
	s_add_u32 s16, s16, s0
	s_addc_u32 s17, s17, 0
	v_readlane_b32 s18, v235, 29
	v_readlane_b32 s19, v235, 30
	v_readlane_b32 s0, v235, 33
	v_readlane_b32 s1, v235, 34
	v_readlane_b32 s20, v235, 31
	v_readlane_b32 s21, v235, 32
	v_readlane_b32 s22, v235, 35
	v_readlane_b32 s23, v235, 36
	s_nop 1
	s_cmp_eq_u32 s13, 0
	s_cselect_b32 s18, s18, s0
	s_cselect_b32 s19, s19, s1
	s_cselect_b32 s20, s20, s22
	s_cselect_b32 s21, s21, s23
	s_cselect_b64 s[6:7], -1, 0
	s_lshl_b32 s0, s11, 9
	s_add_u32 s18, s18, s0
	s_addc_u32 s19, s19, 0
	s_add_u32 s20, s20, s0
	s_addc_u32 s21, s21, 0
	s_mul_i32 s0, s10, 0xa0000
	s_lshl_b32 s1, s11, 8
	s_add_i32 s0, s0, s1
	s_add_u32 s22, s94, s0
	s_addc_u32 s23, s95, 0
	s_lshl_b32 s0, s9, 14
	s_add_u32 s24, s4, s0
	s_addc_u32 s25, s5, 0
	s_add_u32 s26, s68, s0
	s_addc_u32 s27, s69, 0
	v_readlane_b32 s28, v233, 20
	v_readlane_b32 s29, v233, 21
	v_readlane_b32 s30, v233, 22
	v_readlane_b32 s31, v233, 23
	s_nop 1
	s_add_u32 s28, s28, s0
	s_addc_u32 s29, s29, 0
	s_lshl_b32 s0, s9, 9
	s_add_u32 s30, s30, s0
	s_addc_u32 s31, s31, 0
	s_waitcnt lgkmcnt(0)
	s_barrier
	global_load_dword v33, v7, s[16:17]
	global_load_dword v34, v7, s[16:17] offset:2048
	global_load_dword v35, v8, s[16:17]
	global_load_dword v36, v8, s[16:17] offset:2048
	global_load_dword v16, v9, s[18:19]
	global_load_dword v17, v9, s[18:19] offset:2048
	s_add_u32 s18, s18, 0x1000
	s_addc_u32 s19, s19, 0
	global_load_dword v18, v9, s[18:19]
	global_load_dword v19, v9, s[18:19] offset:2048
	s_add_u32 s18, s18, 0x1000
	s_addc_u32 s19, s19, 0
	global_load_dword v20, v9, s[18:19]
	global_load_dword v21, v9, s[18:19] offset:2048
	s_add_u32 s18, s18, 0x1000
	s_addc_u32 s19, s19, 0
	global_load_dword v22, v9, s[18:19]
	global_load_dword v23, v9, s[18:19] offset:2048
	s_add_u32 s18, s18, 0x1000
	s_addc_u32 s19, s19, 0
	global_load_dword v24, v9, s[18:19]
	global_load_dword v25, v9, s[18:19] offset:2048
	s_add_u32 s18, s18, 0x1000
	s_addc_u32 s19, s19, 0
	global_load_dword v26, v9, s[18:19]
	global_load_dword v27, v9, s[18:19] offset:2048
	s_add_u32 s18, s18, 0x1000
	s_addc_u32 s19, s19, 0
	global_load_dword v28, v9, s[18:19]
	global_load_dword v29, v9, s[18:19] offset:2048
	s_add_u32 s18, s18, 0x1000
	s_addc_u32 s19, s19, 0
	global_load_dword v30, v9, s[18:19]
	global_load_dword v31, v9, s[18:19] offset:2048
	global_load_dword v32, v9, s[20:21]
	global_load_ushort v96, v4, s[22:23]
	global_load_ushort v144, v4, s[22:23] offset:1024
	s_add_u32 s22, s22, 0x2800
	s_addc_u32 s23, s23, 0
	global_load_ushort v97, v4, s[22:23]
	global_load_ushort v145, v4, s[22:23] offset:1024
	s_add_u32 s22, s22, 0x2800
	s_addc_u32 s23, s23, 0
	global_load_ushort v98, v4, s[22:23]
	global_load_ushort v146, v4, s[22:23] offset:1024
	s_add_u32 s22, s22, 0x2800
	s_addc_u32 s23, s23, 0
	global_load_ushort v99, v4, s[22:23]
	global_load_ushort v147, v4, s[22:23] offset:1024
	s_add_u32 s22, s22, 0x2800
	s_addc_u32 s23, s23, 0
	global_load_ushort v100, v4, s[22:23]
	global_load_ushort v148, v4, s[22:23] offset:1024
	s_add_u32 s22, s22, 0x2800
	s_addc_u32 s23, s23, 0
	global_load_ushort v101, v4, s[22:23]
	global_load_ushort v149, v4, s[22:23] offset:1024
	s_add_u32 s22, s22, 0x2800
	s_addc_u32 s23, s23, 0
	global_load_ushort v102, v4, s[22:23]
	global_load_ushort v150, v4, s[22:23] offset:1024
	s_add_u32 s22, s22, 0x2800
	s_addc_u32 s23, s23, 0
	global_load_ushort v103, v4, s[22:23]
	global_load_ushort v151, v4, s[22:23] offset:1024
	s_add_u32 s22, s22, 0x2800
	s_addc_u32 s23, s23, 0
	global_load_ushort v104, v4, s[22:23]
	global_load_ushort v152, v4, s[22:23] offset:1024
	s_add_u32 s22, s22, 0x2800
	s_addc_u32 s23, s23, 0
	global_load_ushort v105, v4, s[22:23]
	global_load_ushort v153, v4, s[22:23] offset:1024
	s_add_u32 s22, s22, 0x2800
	s_addc_u32 s23, s23, 0
	global_load_ushort v106, v4, s[22:23]
	global_load_ushort v154, v4, s[22:23] offset:1024
	s_add_u32 s22, s22, 0x2800
	s_addc_u32 s23, s23, 0
	global_load_ushort v107, v4, s[22:23]
	global_load_ushort v155, v4, s[22:23] offset:1024
	s_add_u32 s22, s22, 0x2800
	s_addc_u32 s23, s23, 0
	global_load_ushort v108, v4, s[22:23]
	global_load_ushort v156, v4, s[22:23] offset:1024
	s_add_u32 s22, s22, 0x2800
	s_addc_u32 s23, s23, 0
	global_load_ushort v109, v4, s[22:23]
	global_load_ushort v157, v4, s[22:23] offset:1024
	s_add_u32 s22, s22, 0x2800
	s_addc_u32 s23, s23, 0
	global_load_ushort v110, v4, s[22:23]
	global_load_ushort v158, v4, s[22:23] offset:1024
	s_add_u32 s22, s22, 0x2800
	s_addc_u32 s23, s23, 0
	global_load_ushort v111, v4, s[22:23]
	global_load_ushort v159, v4, s[22:23] offset:1024
	s_add_u32 s22, s22, 0x2800
	s_addc_u32 s23, s23, 0
	s_waitcnt vmcnt(49)
	ds_write_b32 v1, v33
	ds_write_b32 v1, v34 offset:1024
	ds_write_b32 v1, v35 offset:2048
	ds_write_b32 v1, v36 offset:3072
	s_waitcnt lgkmcnt(0)
	s_barrier
; DI float logsig16(float z) { return (fminf(z, 0.f) - __logf(1.f + __expf(-fabsf(z)))) * (1.f / 16.f); }
; DI void phase_gla_prep(const Params& p, int g, char* smem, int bid, int nb) {
;     ...
;     float tsum = 0.f;
;     for (int tt = 0; tt < 32; ++tt) {
;       const float* l = lrs + (half * 32 + tt) * 16; float z = bg;
; #pragma unroll
;       for (int r = 0; r < 16; ++r) z += l[r] * wg[r];
;       tsum += logsig16(z);
;     }
;     tot[half * 128 + d] = tsum;
	v_mov_b32_e32 v54, 0
	ds_read_b128 v[36:39], v2
	ds_read_b128 v[40:43], v2 offset:16
	ds_read_b128 v[44:47], v2 offset:32
	ds_read_b128 v[48:51], v2 offset:48
	ds_read_b128 v[176:179], v2 offset:64
	ds_read_b128 v[180:183], v2 offset:80
	ds_read_b128 v[184:187], v2 offset:96
	ds_read_b128 v[188:191], v2 offset:112
	s_waitcnt vmcnt(32)
	s_waitcnt lgkmcnt(4)
	v_fma_f32 v52, v16, v36, v32
	v_fmac_f32_e32 v52, v17, v37
	v_fmac_f32_e32 v52, v18, v38
	v_fmac_f32_e32 v52, v19, v39
	v_fmac_f32_e32 v52, v20, v40
	v_fmac_f32_e32 v52, v21, v41
	v_fmac_f32_e32 v52, v22, v42
	v_fmac_f32_e32 v52, v23, v43
	v_fmac_f32_e32 v52, v24, v44
	v_fmac_f32_e32 v52, v25, v45
	v_fmac_f32_e32 v52, v26, v46
	v_fmac_f32_e32 v52, v27, v47
	v_fmac_f32_e32 v52, v28, v48
	v_fmac_f32_e32 v52, v29, v49
	v_fmac_f32_e32 v52, v30, v50
	v_fmac_f32_e32 v52, v31, v51
	ds_read_b128 v[36:39], v2 offset:128
	ds_read_b128 v[40:43], v2 offset:144
	ds_read_b128 v[44:47], v2 offset:160
	ds_read_b128 v[48:51], v2 offset:176
	s_waitcnt lgkmcnt(4)
	v_fma_f32 v53, v16, v176, v32
	v_mul_f32_e64 v55, |v52|, s85
	v_fmac_f32_e32 v53, v17, v177
	v_exp_f32_e32 v55, v55
	v_fmac_f32_e32 v53, v18, v178
	v_min_f32_e32 v56, 0, v52
	v_fmac_f32_e32 v53, v19, v179
	v_add_f32_e32 v55, 1.0, v55
	v_fmac_f32_e32 v53, v20, v180
	v_log_f32_e32 v55, v55
	v_fmac_f32_e32 v53, v21, v181
	v_fmac_f32_e32 v53, v22, v182
	v_mul_f32_e32 v57, 0x3f317217, v55
	v_fmac_f32_e32 v53, v23, v183
	v_fma_f32 v58, v55, s74, -v57
	v_fmac_f32_e32 v53, v24, v184
	v_fmac_f32_e32 v58, 0x3377d1cf, v55
	v_fmac_f32_e32 v53, v25, v185
	v_fmac_f32_e32 v58, 0x3f317217, v55
	v_fmac_f32_e32 v53, v26, v186
	v_sub_f32_e32 v56, v56, v58
	v_fmac_f32_e32 v53, v27, v187
	v_mul_f32_e32 v64, 0x3d800000, v56
	v_fmac_f32_e32 v53, v28, v188
	v_add_f32_e32 v54, v54, v64
	v_fmac_f32_e32 v53, v29, v189
	v_fmac_f32_e32 v53, v30, v190
	v_fmac_f32_e32 v53, v31, v191
	ds_read_b128 v[176:179], v2 offset:192
	ds_read_b128 v[180:183], v2 offset:208
	ds_read_b128 v[184:187], v2 offset:224
	ds_read_b128 v[188:191], v2 offset:240
	s_waitcnt lgkmcnt(4)
	v_fma_f32 v52, v16, v36, v32
	v_mul_f32_e64 v55, |v53|, s85
	v_fmac_f32_e32 v52, v17, v37
	v_exp_f32_e32 v55, v55
	v_fmac_f32_e32 v52, v18, v38
	v_min_f32_e32 v56, 0, v53
	v_fmac_f32_e32 v52, v19, v39
	v_add_f32_e32 v55, 1.0, v55
	v_fmac_f32_e32 v52, v20, v40
	v_log_f32_e32 v55, v55
	v_fmac_f32_e32 v52, v21, v41
	v_fmac_f32_e32 v52, v22, v42
	v_mul_f32_e32 v57, 0x3f317217, v55
	v_fmac_f32_e32 v52, v23, v43
	v_fma_f32 v58, v55, s74, -v57
	v_fmac_f32_e32 v52, v24, v44
	v_fmac_f32_e32 v58, 0x3377d1cf, v55
	v_fmac_f32_e32 v52, v25, v45
	v_fmac_f32_e32 v58, 0x3f317217, v55
	v_fmac_f32_e32 v52, v26, v46
	v_sub_f32_e32 v56, v56, v58
	v_fmac_f32_e32 v52, v27, v47
	v_mul_f32_e32 v65, 0x3d800000, v56
	v_fmac_f32_e32 v52, v28, v48
	v_add_f32_e32 v54, v54, v65
	v_fmac_f32_e32 v52, v29, v49
	v_fmac_f32_e32 v52, v30, v50
	v_fmac_f32_e32 v52, v31, v51
	ds_read_b128 v[36:39], v2 offset:256
	ds_read_b128 v[40:43], v2 offset:272
	ds_read_b128 v[44:47], v2 offset:288
	ds_read_b128 v[48:51], v2 offset:304
	s_waitcnt lgkmcnt(4)
	v_fma_f32 v53, v16, v176, v32
	v_mul_f32_e64 v55, |v52|, s85
	v_fmac_f32_e32 v53, v17, v177
	v_exp_f32_e32 v55, v55
	v_fmac_f32_e32 v53, v18, v178
	v_min_f32_e32 v56, 0, v52
	v_fmac_f32_e32 v53, v19, v179
	v_add_f32_e32 v55, 1.0, v55
	v_fmac_f32_e32 v53, v20, v180
	v_log_f32_e32 v55, v55
	v_fmac_f32_e32 v53, v21, v181
	v_fmac_f32_e32 v53, v22, v182
	v_mul_f32_e32 v57, 0x3f317217, v55
	v_fmac_f32_e32 v53, v23, v183
	v_fma_f32 v58, v55, s74, -v57
	v_fmac_f32_e32 v53, v24, v184
	v_fmac_f32_e32 v58, 0x3377d1cf, v55
	v_fmac_f32_e32 v53, v25, v185
	v_fmac_f32_e32 v58, 0x3f317217, v55
	v_fmac_f32_e32 v53, v26, v186
	v_sub_f32_e32 v56, v56, v58
	v_fmac_f32_e32 v53, v27, v187
	v_mul_f32_e32 v66, 0x3d800000, v56
	v_fmac_f32_e32 v53, v28, v188
	v_add_f32_e32 v54, v54, v66
	v_fmac_f32_e32 v53, v29, v189
	v_fmac_f32_e32 v53, v30, v190
	v_fmac_f32_e32 v53, v31, v191
	ds_read_b128 v[176:179], v2 offset:320
	ds_read_b128 v[180:183], v2 offset:336
	ds_read_b128 v[184:187], v2 offset:352
	ds_read_b128 v[188:191], v2 offset:368
	s_waitcnt lgkmcnt(4)
	v_fma_f32 v52, v16, v36, v32
	v_mul_f32_e64 v55, |v53|, s85
	v_fmac_f32_e32 v52, v17, v37
	v_exp_f32_e32 v55, v55
	v_fmac_f32_e32 v52, v18, v38
	v_min_f32_e32 v56, 0, v53
	v_fmac_f32_e32 v52, v19, v39
	v_add_f32_e32 v55, 1.0, v55
	v_fmac_f32_e32 v52, v20, v40
	v_log_f32_e32 v55, v55
	v_fmac_f32_e32 v52, v21, v41
	v_fmac_f32_e32 v52, v22, v42
	v_mul_f32_e32 v57, 0x3f317217, v55
	v_fmac_f32_e32 v52, v23, v43
	v_fma_f32 v58, v55, s74, -v57
	v_fmac_f32_e32 v52, v24, v44
	v_fmac_f32_e32 v58, 0x3377d1cf, v55
	v_fmac_f32_e32 v52, v25, v45
	v_fmac_f32_e32 v58, 0x3f317217, v55
	v_fmac_f32_e32 v52, v26, v46
	v_sub_f32_e32 v56, v56, v58
	v_fmac_f32_e32 v52, v27, v47
	v_mul_f32_e32 v67, 0x3d800000, v56
	v_fmac_f32_e32 v52, v28, v48
	v_add_f32_e32 v54, v54, v67
	v_fmac_f32_e32 v52, v29, v49
	v_fmac_f32_e32 v52, v30, v50
	v_fmac_f32_e32 v52, v31, v51
	ds_read_b128 v[36:39], v2 offset:384
	ds_read_b128 v[40:43], v2 offset:400
	ds_read_b128 v[44:47], v2 offset:416
	ds_read_b128 v[48:51], v2 offset:432
	s_waitcnt lgkmcnt(4)
; DI float logsig16(float z) { return (fminf(z, 0.f) - __logf(1.f + __expf(-fabsf(z)))) * (1.f / 16.f); }
; DI void phase_gla_prep(const Params& p, int g, char* smem, int bid, int nb) {
;     ...
;     float tsum = 0.f;
;     for (int tt = 0; tt < 32; ++tt) {
;       const float* l = lrs + (half * 32 + tt) * 16; float z = bg;
; #pragma unroll
;       for (int r = 0; r < 16; ++r) z += l[r] * wg[r];
;       tsum += logsig16(z);
;     }
;     tot[half * 128 + d] = tsum;
	v_fma_f32 v53, v16, v176, v32
	v_mul_f32_e64 v55, |v52|, s85
	v_fmac_f32_e32 v53, v17, v177
	v_exp_f32_e32 v55, v55
	v_fmac_f32_e32 v53, v18, v178
	v_min_f32_e32 v56, 0, v52
	v_fmac_f32_e32 v53, v19, v179
	v_add_f32_e32 v55, 1.0, v55
	v_fmac_f32_e32 v53, v20, v180
	v_log_f32_e32 v55, v55
	v_fmac_f32_e32 v53, v21, v181
	v_fmac_f32_e32 v53, v22, v182
	v_mul_f32_e32 v57, 0x3f317217, v55
	v_fmac_f32_e32 v53, v23, v183
	v_fma_f32 v58, v55, s74, -v57
	v_fmac_f32_e32 v53, v24, v184
	v_fmac_f32_e32 v58, 0x3377d1cf, v55
	v_fmac_f32_e32 v53, v25, v185
	v_fmac_f32_e32 v58, 0x3f317217, v55
	v_fmac_f32_e32 v53, v26, v186
	v_sub_f32_e32 v56, v56, v58
	v_fmac_f32_e32 v53, v27, v187
	v_mul_f32_e32 v68, 0x3d800000, v56
	v_fmac_f32_e32 v53, v28, v188
	v_add_f32_e32 v54, v54, v68
	v_fmac_f32_e32 v53, v29, v189
	v_fmac_f32_e32 v53, v30, v190
	v_fmac_f32_e32 v53, v31, v191
	ds_read_b128 v[176:179], v2 offset:448
	ds_read_b128 v[180:183], v2 offset:464
	ds_read_b128 v[184:187], v2 offset:480
	ds_read_b128 v[188:191], v2 offset:496
	s_waitcnt lgkmcnt(4)
	v_fma_f32 v52, v16, v36, v32
	v_mul_f32_e64 v55, |v53|, s85
	v_fmac_f32_e32 v52, v17, v37
	v_exp_f32_e32 v55, v55
	v_fmac_f32_e32 v52, v18, v38
	v_min_f32_e32 v56, 0, v53
	v_fmac_f32_e32 v52, v19, v39
	v_add_f32_e32 v55, 1.0, v55
	v_fmac_f32_e32 v52, v20, v40
	v_log_f32_e32 v55, v55
	v_fmac_f32_e32 v52, v21, v41
	v_fmac_f32_e32 v52, v22, v42
	v_mul_f32_e32 v57, 0x3f317217, v55
	v_fmac_f32_e32 v52, v23, v43
	v_fma_f32 v58, v55, s74, -v57
	v_fmac_f32_e32 v52, v24, v44
	v_fmac_f32_e32 v58, 0x3377d1cf, v55
	v_fmac_f32_e32 v52, v25, v45
	v_fmac_f32_e32 v58, 0x3f317217, v55
	v_fmac_f32_e32 v52, v26, v46
	v_sub_f32_e32 v56, v56, v58
	v_fmac_f32_e32 v52, v27, v47
	v_mul_f32_e32 v69, 0x3d800000, v56
	v_fmac_f32_e32 v52, v28, v48
	v_add_f32_e32 v54, v54, v69
	v_fmac_f32_e32 v52, v29, v49
	v_fmac_f32_e32 v52, v30, v50
	v_fmac_f32_e32 v52, v31, v51
	ds_read_b128 v[36:39], v2 offset:512
	ds_read_b128 v[40:43], v2 offset:528
	ds_read_b128 v[44:47], v2 offset:544
	ds_read_b128 v[48:51], v2 offset:560
	s_waitcnt lgkmcnt(4)
	v_fma_f32 v53, v16, v176, v32
	v_mul_f32_e64 v55, |v52|, s85
	v_fmac_f32_e32 v53, v17, v177
	v_exp_f32_e32 v55, v55
	v_fmac_f32_e32 v53, v18, v178
	v_min_f32_e32 v56, 0, v52
	v_fmac_f32_e32 v53, v19, v179
	v_add_f32_e32 v55, 1.0, v55
	v_fmac_f32_e32 v53, v20, v180
	v_log_f32_e32 v55, v55
	v_fmac_f32_e32 v53, v21, v181
	v_fmac_f32_e32 v53, v22, v182
	v_mul_f32_e32 v57, 0x3f317217, v55
	v_fmac_f32_e32 v53, v23, v183
	v_fma_f32 v58, v55, s74, -v57
	v_fmac_f32_e32 v53, v24, v184
	v_fmac_f32_e32 v58, 0x3377d1cf, v55
	v_fmac_f32_e32 v53, v25, v185
	v_fmac_f32_e32 v58, 0x3f317217, v55
	v_fmac_f32_e32 v53, v26, v186
	v_sub_f32_e32 v56, v56, v58
	v_fmac_f32_e32 v53, v27, v187
	v_mul_f32_e32 v70, 0x3d800000, v56
	v_fmac_f32_e32 v53, v28, v188
	v_add_f32_e32 v54, v54, v70
	v_fmac_f32_e32 v53, v29, v189
	v_fmac_f32_e32 v53, v30, v190
	v_fmac_f32_e32 v53, v31, v191
	ds_read_b128 v[176:179], v2 offset:576
	ds_read_b128 v[180:183], v2 offset:592
	ds_read_b128 v[184:187], v2 offset:608
	ds_read_b128 v[188:191], v2 offset:624
	s_waitcnt lgkmcnt(4)
	v_fma_f32 v52, v16, v36, v32
	v_mul_f32_e64 v55, |v53|, s85
	v_fmac_f32_e32 v52, v17, v37
	v_exp_f32_e32 v55, v55
	v_fmac_f32_e32 v52, v18, v38
	v_min_f32_e32 v56, 0, v53
	v_fmac_f32_e32 v52, v19, v39
	v_add_f32_e32 v55, 1.0, v55
	v_fmac_f32_e32 v52, v20, v40
	v_log_f32_e32 v55, v55
	v_fmac_f32_e32 v52, v21, v41
	v_fmac_f32_e32 v52, v22, v42
	v_mul_f32_e32 v57, 0x3f317217, v55
	v_fmac_f32_e32 v52, v23, v43
	v_fma_f32 v58, v55, s74, -v57
	v_fmac_f32_e32 v52, v24, v44
	v_fmac_f32_e32 v58, 0x3377d1cf, v55
	v_fmac_f32_e32 v52, v25, v45
	v_fmac_f32_e32 v58, 0x3f317217, v55
	v_fmac_f32_e32 v52, v26, v46
	v_sub_f32_e32 v56, v56, v58
	v_fmac_f32_e32 v52, v27, v47
	v_mul_f32_e32 v71, 0x3d800000, v56
	v_fmac_f32_e32 v52, v28, v48
	v_add_f32_e32 v54, v54, v71
	v_fmac_f32_e32 v52, v29, v49
	v_fmac_f32_e32 v52, v30, v50
	v_fmac_f32_e32 v52, v31, v51
	ds_read_b128 v[36:39], v2 offset:640
	ds_read_b128 v[40:43], v2 offset:656
	ds_read_b128 v[44:47], v2 offset:672
	ds_read_b128 v[48:51], v2 offset:688
	s_waitcnt lgkmcnt(4)
	v_fma_f32 v53, v16, v176, v32
	v_mul_f32_e64 v55, |v52|, s85
	v_fmac_f32_e32 v53, v17, v177
	v_exp_f32_e32 v55, v55
	v_fmac_f32_e32 v53, v18, v178
	v_min_f32_e32 v56, 0, v52
	v_fmac_f32_e32 v53, v19, v179
	v_add_f32_e32 v55, 1.0, v55
	v_fmac_f32_e32 v53, v20, v180
	v_log_f32_e32 v55, v55
	v_fmac_f32_e32 v53, v21, v181
	v_fmac_f32_e32 v53, v22, v182
	v_mul_f32_e32 v57, 0x3f317217, v55
	v_fmac_f32_e32 v53, v23, v183
	v_fma_f32 v58, v55, s74, -v57
	v_fmac_f32_e32 v53, v24, v184
	v_fmac_f32_e32 v58, 0x3377d1cf, v55
	v_fmac_f32_e32 v53, v25, v185
	v_fmac_f32_e32 v58, 0x3f317217, v55
	v_fmac_f32_e32 v53, v26, v186
	v_sub_f32_e32 v56, v56, v58
	v_fmac_f32_e32 v53, v27, v187
	v_mul_f32_e32 v72, 0x3d800000, v56
	v_fmac_f32_e32 v53, v28, v188
	v_add_f32_e32 v54, v54, v72
	v_fmac_f32_e32 v53, v29, v189
	v_fmac_f32_e32 v53, v30, v190
	v_fmac_f32_e32 v53, v31, v191
	ds_read_b128 v[176:179], v2 offset:704
	ds_read_b128 v[180:183], v2 offset:720
	ds_read_b128 v[184:187], v2 offset:736
	ds_read_b128 v[188:191], v2 offset:752
	s_waitcnt vmcnt(31)
; DI float bf2f(bf16_t v) { return __uint_as_float(((unsigned)v) << 16); }
; DI float logsig16(float z) { return (fminf(z, 0.f) - __logf(1.f + __expf(-fabsf(z)))) * (1.f / 16.f); }
; DI void phase_gla_prep(const Params& p, int g, char* smem, int bid, int nb) {
;     ...
;     float tsum = 0.f;
;     for (int tt = 0; tt < 32; ++tt) {
;       const float* l = lrs + (half * 32 + tt) * 16; float z = bg;
; #pragma unroll
;       for (int r = 0; r < 16; ++r) z += l[r] * wg[r];
;       tsum += logsig16(z);
;     }
;     tot[half * 128 + d] = tsum;
;     ...
;       const float qv = bf2f(proj[tg * NPROJ + PQG + dd]), kv = bf2f(proj[tg * NPROJ + PKG + dd]);
	global_load_ushort v112, v4, s[22:23]
	global_load_ushort v160, v4, s[22:23] offset:1024
	s_add_u32 s22, s22, 0x2800
	s_addc_u32 s23, s23, 0
	global_load_ushort v113, v4, s[22:23]
	global_load_ushort v161, v4, s[22:23] offset:1024
	s_add_u32 s22, s22, 0x2800
	s_addc_u32 s23, s23, 0
	global_load_ushort v114, v4, s[22:23]
	global_load_ushort v162, v4, s[22:23] offset:1024
	s_add_u32 s22, s22, 0x2800
	s_addc_u32 s23, s23, 0
	global_load_ushort v115, v4, s[22:23]
	global_load_ushort v163, v4, s[22:23] offset:1024
	s_add_u32 s22, s22, 0x2800
	s_addc_u32 s23, s23, 0
	global_load_ushort v116, v4, s[22:23]
	global_load_ushort v164, v4, s[22:23] offset:1024
	s_add_u32 s22, s22, 0x2800
	s_addc_u32 s23, s23, 0
	global_load_ushort v117, v4, s[22:23]
	global_load_ushort v165, v4, s[22:23] offset:1024
	s_add_u32 s22, s22, 0x2800
	s_addc_u32 s23, s23, 0
	global_load_ushort v118, v4, s[22:23]
	global_load_ushort v166, v4, s[22:23] offset:1024
	s_add_u32 s22, s22, 0x2800
	s_addc_u32 s23, s23, 0
	global_load_ushort v119, v4, s[22:23]
	global_load_ushort v167, v4, s[22:23] offset:1024
	s_add_u32 s22, s22, 0x2800
	s_addc_u32 s23, s23, 0
	global_load_ushort v120, v4, s[22:23]
	global_load_ushort v168, v4, s[22:23] offset:1024
	s_add_u32 s22, s22, 0x2800
	s_addc_u32 s23, s23, 0
	global_load_ushort v121, v4, s[22:23]
	global_load_ushort v169, v4, s[22:23] offset:1024
	s_add_u32 s22, s22, 0x2800
	s_addc_u32 s23, s23, 0
	global_load_ushort v122, v4, s[22:23]
	global_load_ushort v170, v4, s[22:23] offset:1024
	s_add_u32 s22, s22, 0x2800
	s_addc_u32 s23, s23, 0
	global_load_ushort v123, v4, s[22:23]
	global_load_ushort v171, v4, s[22:23] offset:1024
	s_add_u32 s22, s22, 0x2800
	s_addc_u32 s23, s23, 0
	global_load_ushort v124, v4, s[22:23]
	global_load_ushort v172, v4, s[22:23] offset:1024
	s_add_u32 s22, s22, 0x2800
	s_addc_u32 s23, s23, 0
	global_load_ushort v125, v4, s[22:23]
	global_load_ushort v173, v4, s[22:23] offset:1024
	s_add_u32 s22, s22, 0x2800
	s_addc_u32 s23, s23, 0
	global_load_ushort v126, v4, s[22:23]
	global_load_ushort v174, v4, s[22:23] offset:1024
	s_add_u32 s22, s22, 0x2800
	s_addc_u32 s23, s23, 0
	global_load_ushort v127, v4, s[22:23]
	global_load_ushort v175, v4, s[22:23] offset:1024
	s_add_u32 s22, s22, 0x2800
	s_addc_u32 s23, s23, 0
	s_waitcnt lgkmcnt(4)
	v_fma_f32 v52, v16, v36, v32
	v_mul_f32_e64 v55, |v53|, s85
	v_fmac_f32_e32 v52, v17, v37
	v_exp_f32_e32 v55, v55
	v_fmac_f32_e32 v52, v18, v38
	v_min_f32_e32 v56, 0, v53
	v_fmac_f32_e32 v52, v19, v39
	v_add_f32_e32 v55, 1.0, v55
	v_fmac_f32_e32 v52, v20, v40
	v_log_f32_e32 v55, v55
	v_fmac_f32_e32 v52, v21, v41
	v_fmac_f32_e32 v52, v22, v42
	v_mul_f32_e32 v57, 0x3f317217, v55
	v_fmac_f32_e32 v52, v23, v43
	v_fma_f32 v58, v55, s74, -v57
	v_fmac_f32_e32 v52, v24, v44
	v_fmac_f32_e32 v58, 0x3377d1cf, v55
	v_fmac_f32_e32 v52, v25, v45
	v_fmac_f32_e32 v58, 0x3f317217, v55
	v_fmac_f32_e32 v52, v26, v46
	v_sub_f32_e32 v56, v56, v58
	v_fmac_f32_e32 v52, v27, v47
	v_mul_f32_e32 v73, 0x3d800000, v56
	v_fmac_f32_e32 v52, v28, v48
	v_add_f32_e32 v54, v54, v73
	v_fmac_f32_e32 v52, v29, v49
	v_fmac_f32_e32 v52, v30, v50
	v_fmac_f32_e32 v52, v31, v51
	ds_read_b128 v[36:39], v2 offset:768
	ds_read_b128 v[40:43], v2 offset:784
	ds_read_b128 v[44:47], v2 offset:800
	ds_read_b128 v[48:51], v2 offset:816
	s_waitcnt lgkmcnt(4)
	v_fma_f32 v53, v16, v176, v32
	v_mul_f32_e64 v55, |v52|, s85
	v_fmac_f32_e32 v53, v17, v177
	v_exp_f32_e32 v55, v55
	v_fmac_f32_e32 v53, v18, v178
	v_min_f32_e32 v56, 0, v52
	v_fmac_f32_e32 v53, v19, v179
	v_add_f32_e32 v55, 1.0, v55
	v_fmac_f32_e32 v53, v20, v180
	v_log_f32_e32 v55, v55
	v_fmac_f32_e32 v53, v21, v181
	v_fmac_f32_e32 v53, v22, v182
	v_mul_f32_e32 v57, 0x3f317217, v55
	v_fmac_f32_e32 v53, v23, v183
	v_fma_f32 v58, v55, s74, -v57
	v_fmac_f32_e32 v53, v24, v184
	v_fmac_f32_e32 v58, 0x3377d1cf, v55
	v_fmac_f32_e32 v53, v25, v185
	v_fmac_f32_e32 v58, 0x3f317217, v55
	v_fmac_f32_e32 v53, v26, v186
	v_sub_f32_e32 v56, v56, v58
	v_fmac_f32_e32 v53, v27, v187
	v_mul_f32_e32 v74, 0x3d800000, v56
	v_fmac_f32_e32 v53, v28, v188
	v_add_f32_e32 v54, v54, v74
	v_fmac_f32_e32 v53, v29, v189
	v_fmac_f32_e32 v53, v30, v190
	v_fmac_f32_e32 v53, v31, v191
	ds_read_b128 v[176:179], v2 offset:832
	ds_read_b128 v[180:183], v2 offset:848
	ds_read_b128 v[184:187], v2 offset:864
	ds_read_b128 v[188:191], v2 offset:880
	s_waitcnt lgkmcnt(4)
	v_fma_f32 v52, v16, v36, v32
	v_mul_f32_e64 v55, |v53|, s85
	v_fmac_f32_e32 v52, v17, v37
	v_exp_f32_e32 v55, v55
	v_fmac_f32_e32 v52, v18, v38
	v_min_f32_e32 v56, 0, v53
	v_fmac_f32_e32 v52, v19, v39
	v_add_f32_e32 v55, 1.0, v55
	v_fmac_f32_e32 v52, v20, v40
	v_log_f32_e32 v55, v55
	v_fmac_f32_e32 v52, v21, v41
	v_fmac_f32_e32 v52, v22, v42
	v_mul_f32_e32 v57, 0x3f317217, v55
	v_fmac_f32_e32 v52, v23, v43
	v_fma_f32 v58, v55, s74, -v57
	v_fmac_f32_e32 v52, v24, v44
	v_fmac_f32_e32 v58, 0x3377d1cf, v55
	v_fmac_f32_e32 v52, v25, v45
	v_fmac_f32_e32 v58, 0x3f317217, v55
	v_fmac_f32_e32 v52, v26, v46
	v_sub_f32_e32 v56, v56, v58
	v_fmac_f32_e32 v52, v27, v47
	v_mul_f32_e32 v75, 0x3d800000, v56
	v_fmac_f32_e32 v52, v28, v48
	v_add_f32_e32 v54, v54, v75
	v_fmac_f32_e32 v52, v29, v49
	v_fmac_f32_e32 v52, v30, v50
	v_fmac_f32_e32 v52, v31, v51
	ds_read_b128 v[36:39], v2 offset:896
	ds_read_b128 v[40:43], v2 offset:912
	ds_read_b128 v[44:47], v2 offset:928
	ds_read_b128 v[48:51], v2 offset:944
	s_waitcnt lgkmcnt(4)
; DI float logsig16(float z) { return (fminf(z, 0.f) - __logf(1.f + __expf(-fabsf(z)))) * (1.f / 16.f); }
; DI void phase_gla_prep(const Params& p, int g, char* smem, int bid, int nb) {
;     ...
;     float tsum = 0.f;
;     for (int tt = 0; tt < 32; ++tt) {
;       const float* l = lrs + (half * 32 + tt) * 16; float z = bg;
; #pragma unroll
;       for (int r = 0; r < 16; ++r) z += l[r] * wg[r];
;       tsum += logsig16(z);
;     }
;     tot[half * 128 + d] = tsum;
	v_fma_f32 v53, v16, v176, v32
	v_mul_f32_e64 v55, |v52|, s85
	v_fmac_f32_e32 v53, v17, v177
	v_exp_f32_e32 v55, v55
	v_fmac_f32_e32 v53, v18, v178
	v_min_f32_e32 v56, 0, v52
	v_fmac_f32_e32 v53, v19, v179
	v_add_f32_e32 v55, 1.0, v55
	v_fmac_f32_e32 v53, v20, v180
	v_log_f32_e32 v55, v55
	v_fmac_f32_e32 v53, v21, v181
	v_fmac_f32_e32 v53, v22, v182
	v_mul_f32_e32 v57, 0x3f317217, v55
	v_fmac_f32_e32 v53, v23, v183
	v_fma_f32 v58, v55, s74, -v57
	v_fmac_f32_e32 v53, v24, v184
	v_fmac_f32_e32 v58, 0x3377d1cf, v55
	v_fmac_f32_e32 v53, v25, v185
	v_fmac_f32_e32 v58, 0x3f317217, v55
	v_fmac_f32_e32 v53, v26, v186
	v_sub_f32_e32 v56, v56, v58
	v_fmac_f32_e32 v53, v27, v187
	v_mul_f32_e32 v76, 0x3d800000, v56
	v_fmac_f32_e32 v53, v28, v188
	v_add_f32_e32 v54, v54, v76
	v_fmac_f32_e32 v53, v29, v189
	v_fmac_f32_e32 v53, v30, v190
	v_fmac_f32_e32 v53, v31, v191
	ds_read_b128 v[176:179], v2 offset:960
	ds_read_b128 v[180:183], v2 offset:976
	ds_read_b128 v[184:187], v2 offset:992
	ds_read_b128 v[188:191], v2 offset:1008
	s_waitcnt lgkmcnt(4)
	v_fma_f32 v52, v16, v36, v32
	v_mul_f32_e64 v55, |v53|, s85
	v_fmac_f32_e32 v52, v17, v37
	v_exp_f32_e32 v55, v55
	v_fmac_f32_e32 v52, v18, v38
	v_min_f32_e32 v56, 0, v53
	v_fmac_f32_e32 v52, v19, v39
	v_add_f32_e32 v55, 1.0, v55
	v_fmac_f32_e32 v52, v20, v40
	v_log_f32_e32 v55, v55
	v_fmac_f32_e32 v52, v21, v41
	v_fmac_f32_e32 v52, v22, v42
	v_mul_f32_e32 v57, 0x3f317217, v55
	v_fmac_f32_e32 v52, v23, v43
	v_fma_f32 v58, v55, s74, -v57
	v_fmac_f32_e32 v52, v24, v44
	v_fmac_f32_e32 v58, 0x3377d1cf, v55
	v_fmac_f32_e32 v52, v25, v45
	v_fmac_f32_e32 v58, 0x3f317217, v55
	v_fmac_f32_e32 v52, v26, v46
	v_sub_f32_e32 v56, v56, v58
	v_fmac_f32_e32 v52, v27, v47
	v_mul_f32_e32 v77, 0x3d800000, v56
	v_fmac_f32_e32 v52, v28, v48
	v_add_f32_e32 v54, v54, v77
	v_fmac_f32_e32 v52, v29, v49
	v_fmac_f32_e32 v52, v30, v50
	v_fmac_f32_e32 v52, v31, v51
	ds_read_b128 v[36:39], v2 offset:1024
	ds_read_b128 v[40:43], v2 offset:1040
	ds_read_b128 v[44:47], v2 offset:1056
	ds_read_b128 v[48:51], v2 offset:1072
	s_waitcnt lgkmcnt(4)
	v_fma_f32 v53, v16, v176, v32
	v_mul_f32_e64 v55, |v52|, s85
	v_fmac_f32_e32 v53, v17, v177
	v_exp_f32_e32 v55, v55
	v_fmac_f32_e32 v53, v18, v178
	v_min_f32_e32 v56, 0, v52
	v_fmac_f32_e32 v53, v19, v179
	v_add_f32_e32 v55, 1.0, v55
	v_fmac_f32_e32 v53, v20, v180
	v_log_f32_e32 v55, v55
	v_fmac_f32_e32 v53, v21, v181
	v_fmac_f32_e32 v53, v22, v182
	v_mul_f32_e32 v57, 0x3f317217, v55
	v_fmac_f32_e32 v53, v23, v183
	v_fma_f32 v58, v55, s74, -v57
	v_fmac_f32_e32 v53, v24, v184
	v_fmac_f32_e32 v58, 0x3377d1cf, v55
	v_fmac_f32_e32 v53, v25, v185
	v_fmac_f32_e32 v58, 0x3f317217, v55
	v_fmac_f32_e32 v53, v26, v186
	v_sub_f32_e32 v56, v56, v58
	v_fmac_f32_e32 v53, v27, v187
	v_mul_f32_e32 v78, 0x3d800000, v56
	v_fmac_f32_e32 v53, v28, v188
	v_add_f32_e32 v54, v54, v78
	v_fmac_f32_e32 v53, v29, v189
	v_fmac_f32_e32 v53, v30, v190
	v_fmac_f32_e32 v53, v31, v191
	ds_read_b128 v[176:179], v2 offset:1088
	ds_read_b128 v[180:183], v2 offset:1104
	ds_read_b128 v[184:187], v2 offset:1120
	ds_read_b128 v[188:191], v2 offset:1136
	s_waitcnt lgkmcnt(4)
	v_fma_f32 v52, v16, v36, v32
	v_mul_f32_e64 v55, |v53|, s85
	v_fmac_f32_e32 v52, v17, v37
	v_exp_f32_e32 v55, v55
	v_fmac_f32_e32 v52, v18, v38
	v_min_f32_e32 v56, 0, v53
	v_fmac_f32_e32 v52, v19, v39
	v_add_f32_e32 v55, 1.0, v55
	v_fmac_f32_e32 v52, v20, v40
	v_log_f32_e32 v55, v55
	v_fmac_f32_e32 v52, v21, v41
	v_fmac_f32_e32 v52, v22, v42
	v_mul_f32_e32 v57, 0x3f317217, v55
	v_fmac_f32_e32 v52, v23, v43
	v_fma_f32 v58, v55, s74, -v57
	v_fmac_f32_e32 v52, v24, v44
	v_fmac_f32_e32 v58, 0x3377d1cf, v55
	v_fmac_f32_e32 v52, v25, v45
	v_fmac_f32_e32 v58, 0x3f317217, v55
	v_fmac_f32_e32 v52, v26, v46
	v_sub_f32_e32 v56, v56, v58
	v_fmac_f32_e32 v52, v27, v47
	v_mul_f32_e32 v79, 0x3d800000, v56
	v_fmac_f32_e32 v52, v28, v48
	v_add_f32_e32 v54, v54, v79
	v_fmac_f32_e32 v52, v29, v49
	v_fmac_f32_e32 v52, v30, v50
	v_fmac_f32_e32 v52, v31, v51
	ds_read_b128 v[36:39], v2 offset:1152
	ds_read_b128 v[40:43], v2 offset:1168
	ds_read_b128 v[44:47], v2 offset:1184
	ds_read_b128 v[48:51], v2 offset:1200
	s_waitcnt lgkmcnt(4)
	v_fma_f32 v53, v16, v176, v32
	v_mul_f32_e64 v55, |v52|, s85
	v_fmac_f32_e32 v53, v17, v177
	v_exp_f32_e32 v55, v55
	v_fmac_f32_e32 v53, v18, v178
	v_min_f32_e32 v56, 0, v52
	v_fmac_f32_e32 v53, v19, v179
	v_add_f32_e32 v55, 1.0, v55
	v_fmac_f32_e32 v53, v20, v180
	v_log_f32_e32 v55, v55
	v_fmac_f32_e32 v53, v21, v181
	v_fmac_f32_e32 v53, v22, v182
	v_mul_f32_e32 v57, 0x3f317217, v55
	v_fmac_f32_e32 v53, v23, v183
	v_fma_f32 v58, v55, s74, -v57
	v_fmac_f32_e32 v53, v24, v184
	v_fmac_f32_e32 v58, 0x3377d1cf, v55
	v_fmac_f32_e32 v53, v25, v185
	v_fmac_f32_e32 v58, 0x3f317217, v55
	v_fmac_f32_e32 v53, v26, v186
	v_sub_f32_e32 v56, v56, v58
	v_fmac_f32_e32 v53, v27, v187
	v_mul_f32_e32 v80, 0x3d800000, v56
	v_fmac_f32_e32 v53, v28, v188
	v_add_f32_e32 v54, v54, v80
	v_fmac_f32_e32 v53, v29, v189
	v_fmac_f32_e32 v53, v30, v190
	v_fmac_f32_e32 v53, v31, v191
	ds_read_b128 v[176:179], v2 offset:1216
	ds_read_b128 v[180:183], v2 offset:1232
	ds_read_b128 v[184:187], v2 offset:1248
	ds_read_b128 v[188:191], v2 offset:1264
	s_waitcnt lgkmcnt(4)
; DI float logsig16(float z) { return (fminf(z, 0.f) - __logf(1.f + __expf(-fabsf(z)))) * (1.f / 16.f); }
; DI void phase_gla_prep(const Params& p, int g, char* smem, int bid, int nb) {
;     ...
;     float tsum = 0.f;
;     for (int tt = 0; tt < 32; ++tt) {
;       const float* l = lrs + (half * 32 + tt) * 16; float z = bg;
; #pragma unroll
;       for (int r = 0; r < 16; ++r) z += l[r] * wg[r];
;       tsum += logsig16(z);
;     }
;     tot[half * 128 + d] = tsum;
	v_fma_f32 v52, v16, v36, v32
	v_mul_f32_e64 v55, |v53|, s85
	v_fmac_f32_e32 v52, v17, v37
	v_exp_f32_e32 v55, v55
	v_fmac_f32_e32 v52, v18, v38
	v_min_f32_e32 v56, 0, v53
	v_fmac_f32_e32 v52, v19, v39
	v_add_f32_e32 v55, 1.0, v55
	v_fmac_f32_e32 v52, v20, v40
	v_log_f32_e32 v55, v55
	v_fmac_f32_e32 v52, v21, v41
	v_fmac_f32_e32 v52, v22, v42
	v_mul_f32_e32 v57, 0x3f317217, v55
	v_fmac_f32_e32 v52, v23, v43
	v_fma_f32 v58, v55, s74, -v57
	v_fmac_f32_e32 v52, v24, v44
	v_fmac_f32_e32 v58, 0x3377d1cf, v55
	v_fmac_f32_e32 v52, v25, v45
	v_fmac_f32_e32 v58, 0x3f317217, v55
	v_fmac_f32_e32 v52, v26, v46
	v_sub_f32_e32 v56, v56, v58
	v_fmac_f32_e32 v52, v27, v47
	v_mul_f32_e32 v81, 0x3d800000, v56
	v_fmac_f32_e32 v52, v28, v48
	v_add_f32_e32 v54, v54, v81
	v_fmac_f32_e32 v52, v29, v49
	v_fmac_f32_e32 v52, v30, v50
	v_fmac_f32_e32 v52, v31, v51
	ds_read_b128 v[36:39], v2 offset:1280
	ds_read_b128 v[40:43], v2 offset:1296
	ds_read_b128 v[44:47], v2 offset:1312
	ds_read_b128 v[48:51], v2 offset:1328
	s_waitcnt lgkmcnt(4)
	v_fma_f32 v53, v16, v176, v32
	v_mul_f32_e64 v55, |v52|, s85
	v_fmac_f32_e32 v53, v17, v177
	v_exp_f32_e32 v55, v55
	v_fmac_f32_e32 v53, v18, v178
	v_min_f32_e32 v56, 0, v52
	v_fmac_f32_e32 v53, v19, v179
	v_add_f32_e32 v55, 1.0, v55
	v_fmac_f32_e32 v53, v20, v180
	v_log_f32_e32 v55, v55
	v_fmac_f32_e32 v53, v21, v181
	v_fmac_f32_e32 v53, v22, v182
	v_mul_f32_e32 v57, 0x3f317217, v55
	v_fmac_f32_e32 v53, v23, v183
	v_fma_f32 v58, v55, s74, -v57
	v_fmac_f32_e32 v53, v24, v184
	v_fmac_f32_e32 v58, 0x3377d1cf, v55
	v_fmac_f32_e32 v53, v25, v185
	v_fmac_f32_e32 v58, 0x3f317217, v55
	v_fmac_f32_e32 v53, v26, v186
	v_sub_f32_e32 v56, v56, v58
	v_fmac_f32_e32 v53, v27, v187
	v_mul_f32_e32 v82, 0x3d800000, v56
	v_fmac_f32_e32 v53, v28, v188
	v_add_f32_e32 v54, v54, v82
	v_fmac_f32_e32 v53, v29, v189
	v_fmac_f32_e32 v53, v30, v190
	v_fmac_f32_e32 v53, v31, v191
	ds_read_b128 v[176:179], v2 offset:1344
	ds_read_b128 v[180:183], v2 offset:1360
	ds_read_b128 v[184:187], v2 offset:1376
	ds_read_b128 v[188:191], v2 offset:1392
	s_waitcnt lgkmcnt(4)
	v_fma_f32 v52, v16, v36, v32
	v_mul_f32_e64 v55, |v53|, s85
	v_fmac_f32_e32 v52, v17, v37
	v_exp_f32_e32 v55, v55
	v_fmac_f32_e32 v52, v18, v38
	v_min_f32_e32 v56, 0, v53
	v_fmac_f32_e32 v52, v19, v39
	v_add_f32_e32 v55, 1.0, v55
	v_fmac_f32_e32 v52, v20, v40
	v_log_f32_e32 v55, v55
	v_fmac_f32_e32 v52, v21, v41
	v_fmac_f32_e32 v52, v22, v42
	v_mul_f32_e32 v57, 0x3f317217, v55
	v_fmac_f32_e32 v52, v23, v43
	v_fma_f32 v58, v55, s74, -v57
	v_fmac_f32_e32 v52, v24, v44
	v_fmac_f32_e32 v58, 0x3377d1cf, v55
	v_fmac_f32_e32 v52, v25, v45
	v_fmac_f32_e32 v58, 0x3f317217, v55
	v_fmac_f32_e32 v52, v26, v46
	v_sub_f32_e32 v56, v56, v58
	v_fmac_f32_e32 v52, v27, v47
	v_mul_f32_e32 v83, 0x3d800000, v56
	v_fmac_f32_e32 v52, v28, v48
	v_add_f32_e32 v54, v54, v83
	v_fmac_f32_e32 v52, v29, v49
	v_fmac_f32_e32 v52, v30, v50
	v_fmac_f32_e32 v52, v31, v51
	ds_read_b128 v[36:39], v2 offset:1408
	ds_read_b128 v[40:43], v2 offset:1424
	ds_read_b128 v[44:47], v2 offset:1440
	ds_read_b128 v[48:51], v2 offset:1456
	s_waitcnt lgkmcnt(4)
	v_fma_f32 v53, v16, v176, v32
	v_mul_f32_e64 v55, |v52|, s85
	v_fmac_f32_e32 v53, v17, v177
	v_exp_f32_e32 v55, v55
	v_fmac_f32_e32 v53, v18, v178
	v_min_f32_e32 v56, 0, v52
	v_fmac_f32_e32 v53, v19, v179
	v_add_f32_e32 v55, 1.0, v55
	v_fmac_f32_e32 v53, v20, v180
	v_log_f32_e32 v55, v55
	v_fmac_f32_e32 v53, v21, v181
	v_fmac_f32_e32 v53, v22, v182
	v_mul_f32_e32 v57, 0x3f317217, v55
	v_fmac_f32_e32 v53, v23, v183
	v_fma_f32 v58, v55, s74, -v57
	v_fmac_f32_e32 v53, v24, v184
	v_fmac_f32_e32 v58, 0x3377d1cf, v55
	v_fmac_f32_e32 v53, v25, v185
	v_fmac_f32_e32 v58, 0x3f317217, v55
	v_fmac_f32_e32 v53, v26, v186
	v_sub_f32_e32 v56, v56, v58
	v_fmac_f32_e32 v53, v27, v187
	v_mul_f32_e32 v84, 0x3d800000, v56
	v_fmac_f32_e32 v53, v28, v188
	v_add_f32_e32 v54, v54, v84
	v_fmac_f32_e32 v53, v29, v189
	v_fmac_f32_e32 v53, v30, v190
	v_fmac_f32_e32 v53, v31, v191
	ds_read_b128 v[176:179], v2 offset:1472
	ds_read_b128 v[180:183], v2 offset:1488
	ds_read_b128 v[184:187], v2 offset:1504
	ds_read_b128 v[188:191], v2 offset:1520
	s_waitcnt lgkmcnt(4)
	v_fma_f32 v52, v16, v36, v32
	v_mul_f32_e64 v55, |v53|, s85
	v_fmac_f32_e32 v52, v17, v37
	v_exp_f32_e32 v55, v55
	v_fmac_f32_e32 v52, v18, v38
	v_min_f32_e32 v56, 0, v53
	v_fmac_f32_e32 v52, v19, v39
	v_add_f32_e32 v55, 1.0, v55
	v_fmac_f32_e32 v52, v20, v40
	v_log_f32_e32 v55, v55
	v_fmac_f32_e32 v52, v21, v41
	v_fmac_f32_e32 v52, v22, v42
	v_mul_f32_e32 v57, 0x3f317217, v55
	v_fmac_f32_e32 v52, v23, v43
	v_fma_f32 v58, v55, s74, -v57
	v_fmac_f32_e32 v52, v24, v44
	v_fmac_f32_e32 v58, 0x3377d1cf, v55
	v_fmac_f32_e32 v52, v25, v45
	v_fmac_f32_e32 v58, 0x3f317217, v55
	v_fmac_f32_e32 v52, v26, v46
	v_sub_f32_e32 v56, v56, v58
	v_fmac_f32_e32 v52, v27, v47
	v_mul_f32_e32 v85, 0x3d800000, v56
	v_fmac_f32_e32 v52, v28, v48
	v_add_f32_e32 v54, v54, v85
	v_fmac_f32_e32 v52, v29, v49
	v_fmac_f32_e32 v52, v30, v50
	v_fmac_f32_e32 v52, v31, v51
	ds_read_b128 v[36:39], v2 offset:1536
	ds_read_b128 v[40:43], v2 offset:1552
	ds_read_b128 v[44:47], v2 offset:1568
	ds_read_b128 v[48:51], v2 offset:1584
	s_waitcnt lgkmcnt(4)
; DI float logsig16(float z) { return (fminf(z, 0.f) - __logf(1.f + __expf(-fabsf(z)))) * (1.f / 16.f); }
; DI void phase_gla_prep(const Params& p, int g, char* smem, int bid, int nb) {
;     ...
;     float tsum = 0.f;
;     for (int tt = 0; tt < 32; ++tt) {
;       const float* l = lrs + (half * 32 + tt) * 16; float z = bg;
; #pragma unroll
;       for (int r = 0; r < 16; ++r) z += l[r] * wg[r];
;       tsum += logsig16(z);
;     }
;     tot[half * 128 + d] = tsum;
	v_fma_f32 v53, v16, v176, v32
	v_mul_f32_e64 v55, |v52|, s85
	v_fmac_f32_e32 v53, v17, v177
	v_exp_f32_e32 v55, v55
	v_fmac_f32_e32 v53, v18, v178
	v_min_f32_e32 v56, 0, v52
	v_fmac_f32_e32 v53, v19, v179
	v_add_f32_e32 v55, 1.0, v55
	v_fmac_f32_e32 v53, v20, v180
	v_log_f32_e32 v55, v55
	v_fmac_f32_e32 v53, v21, v181
	v_fmac_f32_e32 v53, v22, v182
	v_mul_f32_e32 v57, 0x3f317217, v55
	v_fmac_f32_e32 v53, v23, v183
	v_fma_f32 v58, v55, s74, -v57
	v_fmac_f32_e32 v53, v24, v184
	v_fmac_f32_e32 v58, 0x3377d1cf, v55
	v_fmac_f32_e32 v53, v25, v185
	v_fmac_f32_e32 v58, 0x3f317217, v55
	v_fmac_f32_e32 v53, v26, v186
	v_sub_f32_e32 v56, v56, v58
	v_fmac_f32_e32 v53, v27, v187
	v_mul_f32_e32 v86, 0x3d800000, v56
	v_fmac_f32_e32 v53, v28, v188
	v_add_f32_e32 v54, v54, v86
	v_fmac_f32_e32 v53, v29, v189
	v_fmac_f32_e32 v53, v30, v190
	v_fmac_f32_e32 v53, v31, v191
	ds_read_b128 v[176:179], v2 offset:1600
	ds_read_b128 v[180:183], v2 offset:1616
	ds_read_b128 v[184:187], v2 offset:1632
	ds_read_b128 v[188:191], v2 offset:1648
	s_waitcnt lgkmcnt(4)
	v_fma_f32 v52, v16, v36, v32
	v_mul_f32_e64 v55, |v53|, s85
	v_fmac_f32_e32 v52, v17, v37
	v_exp_f32_e32 v55, v55
	v_fmac_f32_e32 v52, v18, v38
	v_min_f32_e32 v56, 0, v53
	v_fmac_f32_e32 v52, v19, v39
	v_add_f32_e32 v55, 1.0, v55
	v_fmac_f32_e32 v52, v20, v40
	v_log_f32_e32 v55, v55
	v_fmac_f32_e32 v52, v21, v41
	v_fmac_f32_e32 v52, v22, v42
	v_mul_f32_e32 v57, 0x3f317217, v55
	v_fmac_f32_e32 v52, v23, v43
	v_fma_f32 v58, v55, s74, -v57
	v_fmac_f32_e32 v52, v24, v44
	v_fmac_f32_e32 v58, 0x3377d1cf, v55
	v_fmac_f32_e32 v52, v25, v45
	v_fmac_f32_e32 v58, 0x3f317217, v55
	v_fmac_f32_e32 v52, v26, v46
	v_sub_f32_e32 v56, v56, v58
	v_fmac_f32_e32 v52, v27, v47
	v_mul_f32_e32 v87, 0x3d800000, v56
	v_fmac_f32_e32 v52, v28, v48
	v_add_f32_e32 v54, v54, v87
	v_fmac_f32_e32 v52, v29, v49
	v_fmac_f32_e32 v52, v30, v50
	v_fmac_f32_e32 v52, v31, v51
	ds_read_b128 v[36:39], v2 offset:1664
	ds_read_b128 v[40:43], v2 offset:1680
	ds_read_b128 v[44:47], v2 offset:1696
	ds_read_b128 v[48:51], v2 offset:1712
	s_waitcnt lgkmcnt(4)
	v_fma_f32 v53, v16, v176, v32
	v_mul_f32_e64 v55, |v52|, s85
	v_fmac_f32_e32 v53, v17, v177
	v_exp_f32_e32 v55, v55
	v_fmac_f32_e32 v53, v18, v178
	v_min_f32_e32 v56, 0, v52
	v_fmac_f32_e32 v53, v19, v179
	v_add_f32_e32 v55, 1.0, v55
	v_fmac_f32_e32 v53, v20, v180
	v_log_f32_e32 v55, v55
	v_fmac_f32_e32 v53, v21, v181
	v_fmac_f32_e32 v53, v22, v182
	v_mul_f32_e32 v57, 0x3f317217, v55
	v_fmac_f32_e32 v53, v23, v183
	v_fma_f32 v58, v55, s74, -v57
	v_fmac_f32_e32 v53, v24, v184
	v_fmac_f32_e32 v58, 0x3377d1cf, v55
	v_fmac_f32_e32 v53, v25, v185
	v_fmac_f32_e32 v58, 0x3f317217, v55
	v_fmac_f32_e32 v53, v26, v186
	v_sub_f32_e32 v56, v56, v58
	v_fmac_f32_e32 v53, v27, v187
	v_mul_f32_e32 v88, 0x3d800000, v56
	v_fmac_f32_e32 v53, v28, v188
	v_add_f32_e32 v54, v54, v88
	v_fmac_f32_e32 v53, v29, v189
	v_fmac_f32_e32 v53, v30, v190
	v_fmac_f32_e32 v53, v31, v191
	ds_read_b128 v[176:179], v2 offset:1728
	ds_read_b128 v[180:183], v2 offset:1744
	ds_read_b128 v[184:187], v2 offset:1760
	ds_read_b128 v[188:191], v2 offset:1776
	s_waitcnt lgkmcnt(4)
	v_fma_f32 v52, v16, v36, v32
	v_mul_f32_e64 v55, |v53|, s85
	v_fmac_f32_e32 v52, v17, v37
	v_exp_f32_e32 v55, v55
	v_fmac_f32_e32 v52, v18, v38
	v_min_f32_e32 v56, 0, v53
	v_fmac_f32_e32 v52, v19, v39
	v_add_f32_e32 v55, 1.0, v55
	v_fmac_f32_e32 v52, v20, v40
	v_log_f32_e32 v55, v55
	v_fmac_f32_e32 v52, v21, v41
	v_fmac_f32_e32 v52, v22, v42
	v_mul_f32_e32 v57, 0x3f317217, v55
	v_fmac_f32_e32 v52, v23, v43
	v_fma_f32 v58, v55, s74, -v57
	v_fmac_f32_e32 v52, v24, v44
	v_fmac_f32_e32 v58, 0x3377d1cf, v55
	v_fmac_f32_e32 v52, v25, v45
	v_fmac_f32_e32 v58, 0x3f317217, v55
	v_fmac_f32_e32 v52, v26, v46
	v_sub_f32_e32 v56, v56, v58
	v_fmac_f32_e32 v52, v27, v47
	v_mul_f32_e32 v89, 0x3d800000, v56
	v_fmac_f32_e32 v52, v28, v48
	v_add_f32_e32 v54, v54, v89
	v_fmac_f32_e32 v52, v29, v49
	v_fmac_f32_e32 v52, v30, v50
	v_fmac_f32_e32 v52, v31, v51
	ds_read_b128 v[36:39], v2 offset:1792
	ds_read_b128 v[40:43], v2 offset:1808
	ds_read_b128 v[44:47], v2 offset:1824
	ds_read_b128 v[48:51], v2 offset:1840
	s_waitcnt lgkmcnt(4)
	v_fma_f32 v53, v16, v176, v32
	v_mul_f32_e64 v55, |v52|, s85
	v_fmac_f32_e32 v53, v17, v177
	v_exp_f32_e32 v55, v55
	v_fmac_f32_e32 v53, v18, v178
	v_min_f32_e32 v56, 0, v52
	v_fmac_f32_e32 v53, v19, v179
	v_add_f32_e32 v55, 1.0, v55
	v_fmac_f32_e32 v53, v20, v180
	v_log_f32_e32 v55, v55
	v_fmac_f32_e32 v53, v21, v181
	v_fmac_f32_e32 v53, v22, v182
	v_mul_f32_e32 v57, 0x3f317217, v55
	v_fmac_f32_e32 v53, v23, v183
	v_fma_f32 v58, v55, s74, -v57
	v_fmac_f32_e32 v53, v24, v184
	v_fmac_f32_e32 v58, 0x3377d1cf, v55
	v_fmac_f32_e32 v53, v25, v185
	v_fmac_f32_e32 v58, 0x3f317217, v55
	v_fmac_f32_e32 v53, v26, v186
	v_sub_f32_e32 v56, v56, v58
	v_fmac_f32_e32 v53, v27, v187
	v_mul_f32_e32 v90, 0x3d800000, v56
	v_fmac_f32_e32 v53, v28, v188
	v_add_f32_e32 v54, v54, v90
	v_fmac_f32_e32 v53, v29, v189
	v_fmac_f32_e32 v53, v30, v190
	v_fmac_f32_e32 v53, v31, v191
	ds_read_b128 v[176:179], v2 offset:1856
	ds_read_b128 v[180:183], v2 offset:1872
	ds_read_b128 v[184:187], v2 offset:1888
	ds_read_b128 v[188:191], v2 offset:1904
	s_waitcnt lgkmcnt(4)
; DI float logsig16(float z) { return (fminf(z, 0.f) - __logf(1.f + __expf(-fabsf(z)))) * (1.f / 16.f); }
; DI void phase_gla_prep(const Params& p, int g, char* smem, int bid, int nb) {
;     ...
;     float tsum = 0.f;
;     for (int tt = 0; tt < 32; ++tt) {
;       const float* l = lrs + (half * 32 + tt) * 16; float z = bg;
; #pragma unroll
;       for (int r = 0; r < 16; ++r) z += l[r] * wg[r];
;       tsum += logsig16(z);
;     }
;     tot[half * 128 + d] = tsum;
;     __syncthreads();
	v_fma_f32 v52, v16, v36, v32
	v_mul_f32_e64 v55, |v53|, s85
	v_fmac_f32_e32 v52, v17, v37
	v_exp_f32_e32 v55, v55
	v_fmac_f32_e32 v52, v18, v38
	v_min_f32_e32 v56, 0, v53
	v_fmac_f32_e32 v52, v19, v39
	v_add_f32_e32 v55, 1.0, v55
	v_fmac_f32_e32 v52, v20, v40
	v_log_f32_e32 v55, v55
	v_fmac_f32_e32 v52, v21, v41
	v_fmac_f32_e32 v52, v22, v42
	v_mul_f32_e32 v57, 0x3f317217, v55
	v_fmac_f32_e32 v52, v23, v43
	v_fma_f32 v58, v55, s74, -v57
	v_fmac_f32_e32 v52, v24, v44
	v_fmac_f32_e32 v58, 0x3377d1cf, v55
	v_fmac_f32_e32 v52, v25, v45
	v_fmac_f32_e32 v58, 0x3f317217, v55
	v_fmac_f32_e32 v52, v26, v46
	v_sub_f32_e32 v56, v56, v58
	v_fmac_f32_e32 v52, v27, v47
	v_mul_f32_e32 v91, 0x3d800000, v56
	v_fmac_f32_e32 v52, v28, v48
	v_add_f32_e32 v54, v54, v91
	v_fmac_f32_e32 v52, v29, v49
	v_fmac_f32_e32 v52, v30, v50
	v_fmac_f32_e32 v52, v31, v51
	ds_read_b128 v[36:39], v2 offset:1920
	ds_read_b128 v[40:43], v2 offset:1936
	ds_read_b128 v[44:47], v2 offset:1952
	ds_read_b128 v[48:51], v2 offset:1968
	s_waitcnt lgkmcnt(4)
	v_fma_f32 v53, v16, v176, v32
	v_mul_f32_e64 v55, |v52|, s85
	v_fmac_f32_e32 v53, v17, v177
	v_exp_f32_e32 v55, v55
	v_fmac_f32_e32 v53, v18, v178
	v_min_f32_e32 v56, 0, v52
	v_fmac_f32_e32 v53, v19, v179
	v_add_f32_e32 v55, 1.0, v55
	v_fmac_f32_e32 v53, v20, v180
	v_log_f32_e32 v55, v55
	v_fmac_f32_e32 v53, v21, v181
	v_fmac_f32_e32 v53, v22, v182
	v_mul_f32_e32 v57, 0x3f317217, v55
	v_fmac_f32_e32 v53, v23, v183
	v_fma_f32 v58, v55, s74, -v57
	v_fmac_f32_e32 v53, v24, v184
	v_fmac_f32_e32 v58, 0x3377d1cf, v55
	v_fmac_f32_e32 v53, v25, v185
	v_fmac_f32_e32 v58, 0x3f317217, v55
	v_fmac_f32_e32 v53, v26, v186
	v_sub_f32_e32 v56, v56, v58
	v_fmac_f32_e32 v53, v27, v187
	v_mul_f32_e32 v92, 0x3d800000, v56
	v_fmac_f32_e32 v53, v28, v188
	v_add_f32_e32 v54, v54, v92
	v_fmac_f32_e32 v53, v29, v189
	v_fmac_f32_e32 v53, v30, v190
	v_fmac_f32_e32 v53, v31, v191
	ds_read_b128 v[176:179], v2 offset:1984
	ds_read_b128 v[180:183], v2 offset:2000
	ds_read_b128 v[184:187], v2 offset:2016
	ds_read_b128 v[188:191], v2 offset:2032
	s_waitcnt lgkmcnt(4)
	v_fma_f32 v52, v16, v36, v32
	v_mul_f32_e64 v55, |v53|, s85
	v_fmac_f32_e32 v52, v17, v37
	v_exp_f32_e32 v55, v55
	v_fmac_f32_e32 v52, v18, v38
	v_min_f32_e32 v56, 0, v53
	v_fmac_f32_e32 v52, v19, v39
	v_add_f32_e32 v55, 1.0, v55
	v_fmac_f32_e32 v52, v20, v40
	v_log_f32_e32 v55, v55
	v_fmac_f32_e32 v52, v21, v41
	v_fmac_f32_e32 v52, v22, v42
	v_mul_f32_e32 v57, 0x3f317217, v55
	v_fmac_f32_e32 v52, v23, v43
	v_fma_f32 v58, v55, s74, -v57
	v_fmac_f32_e32 v52, v24, v44
	v_fmac_f32_e32 v58, 0x3377d1cf, v55
	v_fmac_f32_e32 v52, v25, v45
	v_fmac_f32_e32 v58, 0x3f317217, v55
	v_fmac_f32_e32 v52, v26, v46
	v_sub_f32_e32 v56, v56, v58
	v_fmac_f32_e32 v52, v27, v47
	v_mul_f32_e32 v93, 0x3d800000, v56
	v_fmac_f32_e32 v52, v28, v48
	v_add_f32_e32 v54, v54, v93
	v_fmac_f32_e32 v52, v29, v49
	v_fmac_f32_e32 v52, v30, v50
	v_fmac_f32_e32 v52, v31, v51
	s_waitcnt lgkmcnt(0)
	v_fma_f32 v53, v16, v176, v32
	v_mul_f32_e64 v55, |v52|, s85
	v_fmac_f32_e32 v53, v17, v177
	v_exp_f32_e32 v55, v55
	v_fmac_f32_e32 v53, v18, v178
	v_min_f32_e32 v56, 0, v52
	v_fmac_f32_e32 v53, v19, v179
	v_add_f32_e32 v55, 1.0, v55
	v_fmac_f32_e32 v53, v20, v180
	v_log_f32_e32 v55, v55
	v_fmac_f32_e32 v53, v21, v181
	v_fmac_f32_e32 v53, v22, v182
	v_mul_f32_e32 v57, 0x3f317217, v55
	v_fmac_f32_e32 v53, v23, v183
	v_fma_f32 v58, v55, s74, -v57
	v_fmac_f32_e32 v53, v24, v184
	v_fmac_f32_e32 v58, 0x3377d1cf, v55
	v_fmac_f32_e32 v53, v25, v185
	v_fmac_f32_e32 v58, 0x3f317217, v55
	v_fmac_f32_e32 v53, v26, v186
	v_sub_f32_e32 v56, v56, v58
	v_fmac_f32_e32 v53, v27, v187
	v_mul_f32_e32 v94, 0x3d800000, v56
	v_fmac_f32_e32 v53, v28, v188
	v_add_f32_e32 v54, v54, v94
	v_fmac_f32_e32 v53, v29, v189
	v_fmac_f32_e32 v53, v30, v190
	v_fmac_f32_e32 v53, v31, v191
	v_mul_f32_e64 v55, |v53|, s85
	v_exp_f32_e32 v55, v55
	v_min_f32_e32 v56, 0, v53
	v_add_f32_e32 v55, 1.0, v55
	v_log_f32_e32 v55, v55
	s_nop 0
	v_mul_f32_e32 v57, 0x3f317217, v55
	v_fma_f32 v58, v55, s74, -v57
	v_fmac_f32_e32 v58, 0x3377d1cf, v55
	v_fmac_f32_e32 v58, 0x3f317217, v55
	v_sub_f32_e32 v56, v56, v58
	v_mul_f32_e32 v95, 0x3d800000, v56
	v_add_f32_e32 v54, v54, v95
	ds_write_b32 v1, v54 offset:4096
	s_waitcnt lgkmcnt(0)
	s_barrier
; DI float bf2f(bf16_t v) { return __uint_as_float(((unsigned)v) << 16); }
; DI bf16_t f2bf(float x) { return (bf16_t)(pk_bf16(x, 0.f) & 0xffffu); }
; DI float logsig16(float z) { return (fminf(z, 0.f) - __logf(1.f + __expf(-fabsf(z)))) * (1.f / 16.f); }
; DI void phase_gla_prep(const Params& p, int g, char* smem, int bid, int nb) {
;     ...
;     const float t0 = tot[d], t1 = tot[128 + d], TOTAL = t0 + t1;
;     float run = half ? t0 : 0.f;
;     const size_t blk = (size_t)((dir * 4 + head) * 256 + c);
;     unsigned ktp[16];
; #pragma unroll
;     for (int tt = 0; tt < 32; ++tt) {
;       const int t = half * 32 + tt;
;       const float* l = lrs + t * 16; float z = bg;
; #pragma unroll
;       for (int r = 0; r < 16; ++r) z += l[r] * wg[r];
;       const float gv = logsig16(z);
;       const float b = dir ? (TOTAL - run) : (run + gv);
;       run += gv;
;       const size_t tg = (size_t)c * 64 + t;
;       const float qv = bf2f(proj[tg * NPROJ + PQG + dd]), kv = bf2f(proj[tg * NPROJ + PKG + dd]);
;       const float qt = qv * __expf(b) * 0.08838834764831845f, kt = kv * __expf(-b);
;       gq[(blk * 64 + t) * 128 + d] = f2bf(qt);
;       const bf16_t kb = f2bf(kt);
;       gk[(blk * 64 + t) * 128 + d] = kb;
	ds_read_b32 v59, v3 offset:4096
	ds_read_b32 v60, v3 offset:4608
	s_cmp_lg_u32 s8, 0
	s_cselect_b64 s[0:1], -1, 0
	s_waitcnt lgkmcnt(0)
	v_add_f32_e32 v61, v59, v60
	v_cndmask_b32_e64 v62, 0, v59, s[0:1]
	s_waitcnt vmcnt(0)
	v_add_f32_e32 v63, v62, v64
	v_sub_f32_e32 v34, v61, v62
	v_add_f32_e32 v33, v63, v65
	v_sub_f32_e32 v35, v61, v63
	v_cndmask_b32_e64 v34, v34, v63, s[6:7]
	v_cndmask_b32_e64 v35, v35, v33, s[6:7]
	v_mul_f32_e32 v176, 0x3fb8aa3b, v34
	v_mul_f32_e32 v177, 0xbfb8aa3b, v34
	v_mul_f32_e32 v178, 0x3fb8aa3b, v35
	v_mul_f32_e32 v179, 0xbfb8aa3b, v35
	v_exp_f32_e32 v176, v176
	v_exp_f32_e32 v177, v177
	v_exp_f32_e32 v178, v178
	v_exp_f32_e32 v179, v179
	v_lshlrev_b32_e32 v180, 16, v96
	v_lshlrev_b32_e32 v181, 16, v144
	v_lshlrev_b32_e32 v182, 16, v97
	v_lshlrev_b32_e32 v183, 16, v145
	v_mul_f32_e32 v176, v176, v180
	v_mul_f32_e32 v177, v177, v181
	v_mul_f32_e32 v178, v178, v182
	v_mul_f32_e32 v179, v179, v183
	v_mul_f32_e32 v176, 0x3db504f3, v176
	v_mul_f32_e32 v178, 0x3db504f3, v178
	v_cvt_pk_bf16_f32 v180, v176, v178
	v_cvt_pk_bf16_f32 v128, v177, v179
	v_lshrrev_b32_e32 v182, 16, v180
	v_lshrrev_b32_e32 v183, 16, v128
	global_store_short v5, v180, s[24:25]
	global_store_short v5, v128, s[26:27]
	global_store_short v5, v182, s[24:25] offset:16
	global_store_short v5, v183, s[26:27] offset:16
	v_add_f32_e32 v63, v33, v66
	v_sub_f32_e32 v37, v61, v33
	v_add_f32_e32 v36, v63, v67
	v_sub_f32_e32 v38, v61, v63
	v_cndmask_b32_e64 v37, v37, v63, s[6:7]
	v_cndmask_b32_e64 v38, v38, v36, s[6:7]
	v_mul_f32_e32 v184, 0x3fb8aa3b, v37
	v_mul_f32_e32 v185, 0xbfb8aa3b, v37
	v_mul_f32_e32 v186, 0x3fb8aa3b, v38
	v_mul_f32_e32 v187, 0xbfb8aa3b, v38
	v_exp_f32_e32 v184, v184
	v_exp_f32_e32 v185, v185
	v_exp_f32_e32 v186, v186
	v_exp_f32_e32 v187, v187
	v_lshlrev_b32_e32 v188, 16, v98
	v_lshlrev_b32_e32 v189, 16, v146
	v_lshlrev_b32_e32 v190, 16, v99
	v_lshlrev_b32_e32 v191, 16, v147
	v_mul_f32_e32 v184, v184, v188
	v_mul_f32_e32 v185, v185, v189
	v_mul_f32_e32 v186, v186, v190
	v_mul_f32_e32 v187, v187, v191
	v_mul_f32_e32 v184, 0x3db504f3, v184
	v_mul_f32_e32 v186, 0x3db504f3, v186
	v_cvt_pk_bf16_f32 v188, v184, v186
	v_cvt_pk_bf16_f32 v129, v185, v187
	v_lshrrev_b32_e32 v190, 16, v188
	v_lshrrev_b32_e32 v191, 16, v129
	global_store_short v5, v188, s[24:25] offset:32
	global_store_short v5, v129, s[26:27] offset:32
	global_store_short v5, v190, s[24:25] offset:48
	global_store_short v5, v191, s[26:27] offset:48
	v_add_f32_e32 v63, v36, v68
	v_sub_f32_e32 v40, v61, v36
	v_add_f32_e32 v39, v63, v69
	v_sub_f32_e32 v41, v61, v63
	v_cndmask_b32_e64 v40, v40, v63, s[6:7]
	v_cndmask_b32_e64 v41, v41, v39, s[6:7]
	v_mul_f32_e32 v42, 0x3fb8aa3b, v40
	v_mul_f32_e32 v43, 0xbfb8aa3b, v40
	v_mul_f32_e32 v44, 0x3fb8aa3b, v41
	v_mul_f32_e32 v45, 0xbfb8aa3b, v41
	v_exp_f32_e32 v42, v42
	v_exp_f32_e32 v43, v43
	v_exp_f32_e32 v44, v44
	v_exp_f32_e32 v45, v45
	v_lshlrev_b32_e32 v46, 16, v100
	v_lshlrev_b32_e32 v47, 16, v148
	v_lshlrev_b32_e32 v48, 16, v101
	v_lshlrev_b32_e32 v49, 16, v149
	v_mul_f32_e32 v42, v42, v46
	v_mul_f32_e32 v43, v43, v47
	v_mul_f32_e32 v44, v44, v48
	v_mul_f32_e32 v45, v45, v49
	v_mul_f32_e32 v42, 0x3db504f3, v42
	v_mul_f32_e32 v44, 0x3db504f3, v44
	v_cvt_pk_bf16_f32 v46, v42, v44
	v_cvt_pk_bf16_f32 v130, v43, v45
	v_lshrrev_b32_e32 v48, 16, v46
	v_lshrrev_b32_e32 v49, 16, v130
	global_store_short v5, v46, s[24:25] offset:64
	global_store_short v5, v130, s[26:27] offset:64
	global_store_short v5, v48, s[24:25] offset:80
	global_store_short v5, v49, s[26:27] offset:80
	v_add_f32_e32 v63, v39, v70
	v_sub_f32_e32 v51, v61, v39
	v_add_f32_e32 v50, v63, v71
	v_sub_f32_e32 v52, v61, v63
	v_cndmask_b32_e64 v51, v51, v63, s[6:7]
	v_cndmask_b32_e64 v52, v52, v50, s[6:7]
	v_mul_f32_e32 v53, 0x3fb8aa3b, v51
	v_mul_f32_e32 v54, 0xbfb8aa3b, v51
	v_mul_f32_e32 v55, 0x3fb8aa3b, v52
	v_mul_f32_e32 v56, 0xbfb8aa3b, v52
	v_exp_f32_e32 v53, v53
	v_exp_f32_e32 v54, v54
	v_exp_f32_e32 v55, v55
	v_exp_f32_e32 v56, v56
	v_lshlrev_b32_e32 v57, 16, v102
	v_lshlrev_b32_e32 v58, 16, v150
	v_lshlrev_b32_e32 v59, 16, v103
	v_lshlrev_b32_e32 v60, 16, v151
	v_mul_f32_e32 v53, v53, v57
	v_mul_f32_e32 v54, v54, v58
	v_mul_f32_e32 v55, v55, v59
	v_mul_f32_e32 v56, v56, v60
	v_mul_f32_e32 v53, 0x3db504f3, v53
	v_mul_f32_e32 v55, 0x3db504f3, v55
	v_cvt_pk_bf16_f32 v57, v53, v55
	v_cvt_pk_bf16_f32 v131, v54, v56
	v_lshrrev_b32_e32 v59, 16, v57
	v_lshrrev_b32_e32 v60, 16, v131
	global_store_short v5, v57, s[24:25] offset:96
	global_store_short v5, v131, s[26:27] offset:96
	global_store_short v5, v59, s[24:25] offset:112
	global_store_short v5, v60, s[26:27] offset:112
	v_add_f32_e32 v63, v50, v72
	v_sub_f32_e32 v34, v61, v50
	v_add_f32_e32 v33, v63, v73
	v_sub_f32_e32 v35, v61, v63
	v_cndmask_b32_e64 v34, v34, v63, s[6:7]
	v_cndmask_b32_e64 v35, v35, v33, s[6:7]
	v_mul_f32_e32 v176, 0x3fb8aa3b, v34
	v_mul_f32_e32 v177, 0xbfb8aa3b, v34
	v_mul_f32_e32 v178, 0x3fb8aa3b, v35
	v_mul_f32_e32 v179, 0xbfb8aa3b, v35
	v_exp_f32_e32 v176, v176
	v_exp_f32_e32 v177, v177
	v_exp_f32_e32 v178, v178
	v_exp_f32_e32 v179, v179
	v_lshlrev_b32_e32 v180, 16, v104
	v_lshlrev_b32_e32 v181, 16, v152
	v_lshlrev_b32_e32 v182, 16, v105
	v_lshlrev_b32_e32 v183, 16, v153
	v_mul_f32_e32 v176, v176, v180
	v_mul_f32_e32 v177, v177, v181
	v_mul_f32_e32 v178, v178, v182
	v_mul_f32_e32 v179, v179, v183
	v_mul_f32_e32 v176, 0x3db504f3, v176
	v_mul_f32_e32 v178, 0x3db504f3, v178
	v_cvt_pk_bf16_f32 v180, v176, v178
	v_cvt_pk_bf16_f32 v132, v177, v179
	v_lshrrev_b32_e32 v182, 16, v180
	v_lshrrev_b32_e32 v183, 16, v132
	global_store_short v5, v180, s[24:25] offset:128
	global_store_short v5, v132, s[26:27] offset:128
; DI float bf2f(bf16_t v) { return __uint_as_float(((unsigned)v) << 16); }
; DI bf16_t f2bf(float x) { return (bf16_t)(pk_bf16(x, 0.f) & 0xffffu); }
; DI float logsig16(float z) { return (fminf(z, 0.f) - __logf(1.f + __expf(-fabsf(z)))) * (1.f / 16.f); }
; DI void phase_gla_prep(const Params& p, int g, char* smem, int bid, int nb) {
;     ...
;     for (int tt = 0; tt < 32; ++tt) {
;       const int t = half * 32 + tt;
;       const float* l = lrs + t * 16; float z = bg;
; #pragma unroll
;       for (int r = 0; r < 16; ++r) z += l[r] * wg[r];
;       const float gv = logsig16(z);
;       const float b = dir ? (TOTAL - run) : (run + gv);
;       run += gv;
;       const size_t tg = (size_t)c * 64 + t;
;       const float qv = bf2f(proj[tg * NPROJ + PQG + dd]), kv = bf2f(proj[tg * NPROJ + PKG + dd]);
;       const float qt = qv * __expf(b) * 0.08838834764831845f, kt = kv * __expf(-b);
;       gq[(blk * 64 + t) * 128 + d] = f2bf(qt);
;       const bf16_t kb = f2bf(kt);
;       gk[(blk * 64 + t) * 128 + d] = kb;
;       if (tt & 1) ktp[tt >> 1] |= ((unsigned)kb) << 16; else ktp[tt >> 1] = kb;
;     }
	global_store_short v5, v182, s[24:25] offset:144
	global_store_short v5, v183, s[26:27] offset:144
	v_add_f32_e32 v63, v33, v74
	v_sub_f32_e32 v37, v61, v33
	v_add_f32_e32 v36, v63, v75
	v_sub_f32_e32 v38, v61, v63
	v_cndmask_b32_e64 v37, v37, v63, s[6:7]
	v_cndmask_b32_e64 v38, v38, v36, s[6:7]
	v_mul_f32_e32 v184, 0x3fb8aa3b, v37
	v_mul_f32_e32 v185, 0xbfb8aa3b, v37
	v_mul_f32_e32 v186, 0x3fb8aa3b, v38
	v_mul_f32_e32 v187, 0xbfb8aa3b, v38
	v_exp_f32_e32 v184, v184
	v_exp_f32_e32 v185, v185
	v_exp_f32_e32 v186, v186
	v_exp_f32_e32 v187, v187
	v_lshlrev_b32_e32 v188, 16, v106
	v_lshlrev_b32_e32 v189, 16, v154
	v_lshlrev_b32_e32 v190, 16, v107
	v_lshlrev_b32_e32 v191, 16, v155
	v_mul_f32_e32 v184, v184, v188
	v_mul_f32_e32 v185, v185, v189
	v_mul_f32_e32 v186, v186, v190
	v_mul_f32_e32 v187, v187, v191
	v_mul_f32_e32 v184, 0x3db504f3, v184
	v_mul_f32_e32 v186, 0x3db504f3, v186
	v_cvt_pk_bf16_f32 v188, v184, v186
	v_cvt_pk_bf16_f32 v133, v185, v187
	v_lshrrev_b32_e32 v190, 16, v188
	v_lshrrev_b32_e32 v191, 16, v133
	global_store_short v5, v188, s[24:25] offset:160
	global_store_short v5, v133, s[26:27] offset:160
	global_store_short v5, v190, s[24:25] offset:176
	global_store_short v5, v191, s[26:27] offset:176
	v_add_f32_e32 v63, v36, v76
	v_sub_f32_e32 v40, v61, v36
	v_add_f32_e32 v39, v63, v77
	v_sub_f32_e32 v41, v61, v63
	v_cndmask_b32_e64 v40, v40, v63, s[6:7]
	v_cndmask_b32_e64 v41, v41, v39, s[6:7]
	v_mul_f32_e32 v42, 0x3fb8aa3b, v40
	v_mul_f32_e32 v43, 0xbfb8aa3b, v40
	v_mul_f32_e32 v44, 0x3fb8aa3b, v41
	v_mul_f32_e32 v45, 0xbfb8aa3b, v41
	v_exp_f32_e32 v42, v42
	v_exp_f32_e32 v43, v43
	v_exp_f32_e32 v44, v44
	v_exp_f32_e32 v45, v45
	v_lshlrev_b32_e32 v46, 16, v108
	v_lshlrev_b32_e32 v47, 16, v156
	v_lshlrev_b32_e32 v48, 16, v109
	v_lshlrev_b32_e32 v49, 16, v157
	v_mul_f32_e32 v42, v42, v46
	v_mul_f32_e32 v43, v43, v47
	v_mul_f32_e32 v44, v44, v48
	v_mul_f32_e32 v45, v45, v49
	v_mul_f32_e32 v42, 0x3db504f3, v42
	v_mul_f32_e32 v44, 0x3db504f3, v44
	v_cvt_pk_bf16_f32 v46, v42, v44
	v_cvt_pk_bf16_f32 v134, v43, v45
	v_lshrrev_b32_e32 v48, 16, v46
	v_lshrrev_b32_e32 v49, 16, v134
	global_store_short v5, v46, s[24:25] offset:192
	global_store_short v5, v134, s[26:27] offset:192
	global_store_short v5, v48, s[24:25] offset:208
	global_store_short v5, v49, s[26:27] offset:208
	v_add_f32_e32 v63, v39, v78
	v_sub_f32_e32 v51, v61, v39
	v_add_f32_e32 v50, v63, v79
	v_sub_f32_e32 v52, v61, v63
	v_cndmask_b32_e64 v51, v51, v63, s[6:7]
	v_cndmask_b32_e64 v52, v52, v50, s[6:7]
	v_mul_f32_e32 v53, 0x3fb8aa3b, v51
	v_mul_f32_e32 v54, 0xbfb8aa3b, v51
	v_mul_f32_e32 v55, 0x3fb8aa3b, v52
	v_mul_f32_e32 v56, 0xbfb8aa3b, v52
	v_exp_f32_e32 v53, v53
	v_exp_f32_e32 v54, v54
	v_exp_f32_e32 v55, v55
	v_exp_f32_e32 v56, v56
	v_lshlrev_b32_e32 v57, 16, v110
	v_lshlrev_b32_e32 v58, 16, v158
	v_lshlrev_b32_e32 v59, 16, v111
	v_lshlrev_b32_e32 v60, 16, v159
	v_mul_f32_e32 v53, v53, v57
	v_mul_f32_e32 v54, v54, v58
	v_mul_f32_e32 v55, v55, v59
	v_mul_f32_e32 v56, v56, v60
	v_mul_f32_e32 v53, 0x3db504f3, v53
	v_mul_f32_e32 v55, 0x3db504f3, v55
	v_cvt_pk_bf16_f32 v57, v53, v55
	v_cvt_pk_bf16_f32 v135, v54, v56
	v_lshrrev_b32_e32 v59, 16, v57
	v_lshrrev_b32_e32 v60, 16, v135
	global_store_short v5, v57, s[24:25] offset:224
	global_store_short v5, v135, s[26:27] offset:224
	global_store_short v5, v59, s[24:25] offset:240
	global_store_short v5, v60, s[26:27] offset:240
	v_add_f32_e32 v63, v50, v80
	v_sub_f32_e32 v34, v61, v50
	v_add_f32_e32 v33, v63, v81
	v_sub_f32_e32 v35, v61, v63
	v_cndmask_b32_e64 v34, v34, v63, s[6:7]
	v_cndmask_b32_e64 v35, v35, v33, s[6:7]
	v_mul_f32_e32 v176, 0x3fb8aa3b, v34
	v_mul_f32_e32 v177, 0xbfb8aa3b, v34
	v_mul_f32_e32 v178, 0x3fb8aa3b, v35
	v_mul_f32_e32 v179, 0xbfb8aa3b, v35
	v_exp_f32_e32 v176, v176
	v_exp_f32_e32 v177, v177
	v_exp_f32_e32 v178, v178
	v_exp_f32_e32 v179, v179
	v_lshlrev_b32_e32 v180, 16, v112
	v_lshlrev_b32_e32 v181, 16, v160
	v_lshlrev_b32_e32 v182, 16, v113
	v_lshlrev_b32_e32 v183, 16, v161
	v_mul_f32_e32 v176, v176, v180
	v_mul_f32_e32 v177, v177, v181
	v_mul_f32_e32 v178, v178, v182
	v_mul_f32_e32 v179, v179, v183
	v_mul_f32_e32 v176, 0x3db504f3, v176
	v_mul_f32_e32 v178, 0x3db504f3, v178
	v_cvt_pk_bf16_f32 v180, v176, v178
	v_cvt_pk_bf16_f32 v136, v177, v179
	v_lshrrev_b32_e32 v182, 16, v180
	v_lshrrev_b32_e32 v183, 16, v136
	global_store_short v5, v180, s[24:25] offset:256
	global_store_short v5, v136, s[26:27] offset:256
	global_store_short v5, v182, s[24:25] offset:272
	global_store_short v5, v183, s[26:27] offset:272
	v_add_f32_e32 v63, v33, v82
	v_sub_f32_e32 v37, v61, v33
	v_add_f32_e32 v36, v63, v83
	v_sub_f32_e32 v38, v61, v63
	v_cndmask_b32_e64 v37, v37, v63, s[6:7]
	v_cndmask_b32_e64 v38, v38, v36, s[6:7]
	v_mul_f32_e32 v184, 0x3fb8aa3b, v37
	v_mul_f32_e32 v185, 0xbfb8aa3b, v37
	v_mul_f32_e32 v186, 0x3fb8aa3b, v38
	v_mul_f32_e32 v187, 0xbfb8aa3b, v38
	v_exp_f32_e32 v184, v184
	v_exp_f32_e32 v185, v185
	v_exp_f32_e32 v186, v186
	v_exp_f32_e32 v187, v187
	v_lshlrev_b32_e32 v188, 16, v114
	v_lshlrev_b32_e32 v189, 16, v162
	v_lshlrev_b32_e32 v190, 16, v115
	v_lshlrev_b32_e32 v191, 16, v163
	v_mul_f32_e32 v184, v184, v188
	v_mul_f32_e32 v185, v185, v189
	v_mul_f32_e32 v186, v186, v190
	v_mul_f32_e32 v187, v187, v191
	v_mul_f32_e32 v184, 0x3db504f3, v184
	v_mul_f32_e32 v186, 0x3db504f3, v186
	v_cvt_pk_bf16_f32 v188, v184, v186
	v_cvt_pk_bf16_f32 v137, v185, v187
	v_lshrrev_b32_e32 v190, 16, v188
	v_lshrrev_b32_e32 v191, 16, v137
	global_store_short v5, v188, s[24:25] offset:288
	global_store_short v5, v137, s[26:27] offset:288
	global_store_short v5, v190, s[24:25] offset:304
	global_store_short v5, v191, s[26:27] offset:304
; DI float bf2f(bf16_t v) { return __uint_as_float(((unsigned)v) << 16); }
; DI bf16_t f2bf(float x) { return (bf16_t)(pk_bf16(x, 0.f) & 0xffffu); }
; DI float logsig16(float z) { return (fminf(z, 0.f) - __logf(1.f + __expf(-fabsf(z)))) * (1.f / 16.f); }
; DI void phase_gla_prep(const Params& p, int g, char* smem, int bid, int nb) {
;     ...
;     for (int tt = 0; tt < 32; ++tt) {
;       const int t = half * 32 + tt;
;       const float* l = lrs + t * 16; float z = bg;
; #pragma unroll
;       for (int r = 0; r < 16; ++r) z += l[r] * wg[r];
;       const float gv = logsig16(z);
;       const float b = dir ? (TOTAL - run) : (run + gv);
;       run += gv;
;       const size_t tg = (size_t)c * 64 + t;
;       const float qv = bf2f(proj[tg * NPROJ + PQG + dd]), kv = bf2f(proj[tg * NPROJ + PKG + dd]);
;       const float qt = qv * __expf(b) * 0.08838834764831845f, kt = kv * __expf(-b);
;       gq[(blk * 64 + t) * 128 + d] = f2bf(qt);
;       const bf16_t kb = f2bf(kt);
;       gk[(blk * 64 + t) * 128 + d] = kb;
;       if (tt & 1) ktp[tt >> 1] |= ((unsigned)kb) << 16; else ktp[tt >> 1] = kb;
;     }
;     bf16_t* kd = gkt + (blk * 128 + d) * 64 + half * 32;
; #pragma unroll
;     for (int q = 0; q < 4; ++q) { u32x4 v = {ktp[4 * q], ktp[4 * q + 1], ktp[4 * q + 2], ktp[4 * q + 3]}; *(u32x4*)(kd + 8 * q) = v; }
;     if (half == 0) ge[blk * 128 + d] = __expf(TOTAL);
	v_add_f32_e32 v63, v36, v84
	v_sub_f32_e32 v40, v61, v36
	v_add_f32_e32 v39, v63, v85
	v_sub_f32_e32 v41, v61, v63
	v_cndmask_b32_e64 v40, v40, v63, s[6:7]
	v_cndmask_b32_e64 v41, v41, v39, s[6:7]
	v_mul_f32_e32 v42, 0x3fb8aa3b, v40
	v_mul_f32_e32 v43, 0xbfb8aa3b, v40
	v_mul_f32_e32 v44, 0x3fb8aa3b, v41
	v_mul_f32_e32 v45, 0xbfb8aa3b, v41
	v_exp_f32_e32 v42, v42
	v_exp_f32_e32 v43, v43
	v_exp_f32_e32 v44, v44
	v_exp_f32_e32 v45, v45
	v_lshlrev_b32_e32 v46, 16, v116
	v_lshlrev_b32_e32 v47, 16, v164
	v_lshlrev_b32_e32 v48, 16, v117
	v_lshlrev_b32_e32 v49, 16, v165
	v_mul_f32_e32 v42, v42, v46
	v_mul_f32_e32 v43, v43, v47
	v_mul_f32_e32 v44, v44, v48
	v_mul_f32_e32 v45, v45, v49
	v_mul_f32_e32 v42, 0x3db504f3, v42
	v_mul_f32_e32 v44, 0x3db504f3, v44
	v_cvt_pk_bf16_f32 v46, v42, v44
	v_cvt_pk_bf16_f32 v138, v43, v45
	v_lshrrev_b32_e32 v48, 16, v46
	v_lshrrev_b32_e32 v49, 16, v138
	global_store_short v5, v46, s[24:25] offset:320
	global_store_short v5, v138, s[26:27] offset:320
	global_store_short v5, v48, s[24:25] offset:336
	global_store_short v5, v49, s[26:27] offset:336
	v_add_f32_e32 v63, v39, v86
	v_sub_f32_e32 v51, v61, v39
	v_add_f32_e32 v50, v63, v87
	v_sub_f32_e32 v52, v61, v63
	v_cndmask_b32_e64 v51, v51, v63, s[6:7]
	v_cndmask_b32_e64 v52, v52, v50, s[6:7]
	v_mul_f32_e32 v53, 0x3fb8aa3b, v51
	v_mul_f32_e32 v54, 0xbfb8aa3b, v51
	v_mul_f32_e32 v55, 0x3fb8aa3b, v52
	v_mul_f32_e32 v56, 0xbfb8aa3b, v52
	v_exp_f32_e32 v53, v53
	v_exp_f32_e32 v54, v54
	v_exp_f32_e32 v55, v55
	v_exp_f32_e32 v56, v56
	v_lshlrev_b32_e32 v57, 16, v118
	v_lshlrev_b32_e32 v58, 16, v166
	v_lshlrev_b32_e32 v59, 16, v119
	v_lshlrev_b32_e32 v60, 16, v167
	v_mul_f32_e32 v53, v53, v57
	v_mul_f32_e32 v54, v54, v58
	v_mul_f32_e32 v55, v55, v59
	v_mul_f32_e32 v56, v56, v60
	v_mul_f32_e32 v53, 0x3db504f3, v53
	v_mul_f32_e32 v55, 0x3db504f3, v55
	v_cvt_pk_bf16_f32 v57, v53, v55
	v_cvt_pk_bf16_f32 v139, v54, v56
	v_lshrrev_b32_e32 v59, 16, v57
	v_lshrrev_b32_e32 v60, 16, v139
	global_store_short v5, v57, s[24:25] offset:352
	global_store_short v5, v139, s[26:27] offset:352
	global_store_short v5, v59, s[24:25] offset:368
	global_store_short v5, v60, s[26:27] offset:368
	v_add_f32_e32 v63, v50, v88
	v_sub_f32_e32 v34, v61, v50
	v_add_f32_e32 v33, v63, v89
	v_sub_f32_e32 v35, v61, v63
	v_cndmask_b32_e64 v34, v34, v63, s[6:7]
	v_cndmask_b32_e64 v35, v35, v33, s[6:7]
	v_mul_f32_e32 v176, 0x3fb8aa3b, v34
	v_mul_f32_e32 v177, 0xbfb8aa3b, v34
	v_mul_f32_e32 v178, 0x3fb8aa3b, v35
	v_mul_f32_e32 v179, 0xbfb8aa3b, v35
	v_exp_f32_e32 v176, v176
	v_exp_f32_e32 v177, v177
	v_exp_f32_e32 v178, v178
	v_exp_f32_e32 v179, v179
	v_lshlrev_b32_e32 v180, 16, v120
	v_lshlrev_b32_e32 v181, 16, v168
	v_lshlrev_b32_e32 v182, 16, v121
	v_lshlrev_b32_e32 v183, 16, v169
	v_mul_f32_e32 v176, v176, v180
	v_mul_f32_e32 v177, v177, v181
	v_mul_f32_e32 v178, v178, v182
	v_mul_f32_e32 v179, v179, v183
	v_mul_f32_e32 v176, 0x3db504f3, v176
	v_mul_f32_e32 v178, 0x3db504f3, v178
	v_cvt_pk_bf16_f32 v180, v176, v178
	v_cvt_pk_bf16_f32 v140, v177, v179
	v_lshrrev_b32_e32 v182, 16, v180
	v_lshrrev_b32_e32 v183, 16, v140
	global_store_short v5, v180, s[24:25] offset:384
	global_store_short v5, v140, s[26:27] offset:384
	global_store_short v5, v182, s[24:25] offset:400
	global_store_short v5, v183, s[26:27] offset:400
	v_add_f32_e32 v63, v33, v90
	v_sub_f32_e32 v37, v61, v33
	v_add_f32_e32 v36, v63, v91
	v_sub_f32_e32 v38, v61, v63
	v_cndmask_b32_e64 v37, v37, v63, s[6:7]
	v_cndmask_b32_e64 v38, v38, v36, s[6:7]
	v_mul_f32_e32 v184, 0x3fb8aa3b, v37
	v_mul_f32_e32 v185, 0xbfb8aa3b, v37
	v_mul_f32_e32 v186, 0x3fb8aa3b, v38
	v_mul_f32_e32 v187, 0xbfb8aa3b, v38
	v_exp_f32_e32 v184, v184
	v_exp_f32_e32 v185, v185
	v_exp_f32_e32 v186, v186
	v_exp_f32_e32 v187, v187
	v_lshlrev_b32_e32 v188, 16, v122
	v_lshlrev_b32_e32 v189, 16, v170
	v_lshlrev_b32_e32 v190, 16, v123
	v_lshlrev_b32_e32 v191, 16, v171
	v_mul_f32_e32 v184, v184, v188
	v_mul_f32_e32 v185, v185, v189
	v_mul_f32_e32 v186, v186, v190
	v_mul_f32_e32 v187, v187, v191
	v_mul_f32_e32 v184, 0x3db504f3, v184
	v_mul_f32_e32 v186, 0x3db504f3, v186
	v_cvt_pk_bf16_f32 v188, v184, v186
	v_cvt_pk_bf16_f32 v141, v185, v187
	v_lshrrev_b32_e32 v190, 16, v188
	v_lshrrev_b32_e32 v191, 16, v141
	global_store_short v5, v188, s[24:25] offset:416
	global_store_short v5, v141, s[26:27] offset:416
	global_store_short v5, v190, s[24:25] offset:432
	global_store_short v5, v191, s[26:27] offset:432
	v_add_f32_e32 v63, v36, v92
	v_sub_f32_e32 v40, v61, v36
	v_add_f32_e32 v39, v63, v93
	v_sub_f32_e32 v41, v61, v63
	v_cndmask_b32_e64 v40, v40, v63, s[6:7]
	v_cndmask_b32_e64 v41, v41, v39, s[6:7]
	v_mul_f32_e32 v42, 0x3fb8aa3b, v40
	v_mul_f32_e32 v43, 0xbfb8aa3b, v40
	v_mul_f32_e32 v44, 0x3fb8aa3b, v41
	v_mul_f32_e32 v45, 0xbfb8aa3b, v41
	v_exp_f32_e32 v42, v42
	v_exp_f32_e32 v43, v43
	v_exp_f32_e32 v44, v44
	v_exp_f32_e32 v45, v45
	v_lshlrev_b32_e32 v46, 16, v124
	v_lshlrev_b32_e32 v47, 16, v172
	v_lshlrev_b32_e32 v48, 16, v125
	v_lshlrev_b32_e32 v49, 16, v173
	v_mul_f32_e32 v42, v42, v46
	v_mul_f32_e32 v43, v43, v47
	v_mul_f32_e32 v44, v44, v48
	v_mul_f32_e32 v45, v45, v49
	v_mul_f32_e32 v42, 0x3db504f3, v42
	v_mul_f32_e32 v44, 0x3db504f3, v44
	v_cvt_pk_bf16_f32 v46, v42, v44
	v_cvt_pk_bf16_f32 v142, v43, v45
	v_lshrrev_b32_e32 v48, 16, v46
	v_lshrrev_b32_e32 v49, 16, v142
	global_store_short v5, v46, s[24:25] offset:448
	global_store_short v5, v142, s[26:27] offset:448
	global_store_short v5, v48, s[24:25] offset:464
	global_store_short v5, v49, s[26:27] offset:464
	v_add_f32_e32 v63, v39, v94
	v_sub_f32_e32 v51, v61, v39
	v_add_f32_e32 v50, v63, v95
	v_sub_f32_e32 v52, v61, v63
	v_cndmask_b32_e64 v51, v51, v63, s[6:7]
	v_cndmask_b32_e64 v52, v52, v50, s[6:7]
	v_mul_f32_e32 v53, 0x3fb8aa3b, v51
	v_mul_f32_e32 v54, 0xbfb8aa3b, v51
	v_mul_f32_e32 v55, 0x3fb8aa3b, v52
	v_mul_f32_e32 v56, 0xbfb8aa3b, v52
	v_exp_f32_e32 v53, v53
	v_exp_f32_e32 v54, v54
	v_exp_f32_e32 v55, v55
	v_exp_f32_e32 v56, v56
	v_lshlrev_b32_e32 v57, 16, v126
	v_lshlrev_b32_e32 v58, 16, v174
	v_lshlrev_b32_e32 v59, 16, v127
	v_lshlrev_b32_e32 v60, 16, v175
	v_mul_f32_e32 v53, v53, v57
	v_mul_f32_e32 v54, v54, v58
	v_mul_f32_e32 v55, v55, v59
	v_mul_f32_e32 v56, v56, v60
	v_mul_f32_e32 v53, 0x3db504f3, v53
	v_mul_f32_e32 v55, 0x3db504f3, v55
	v_cvt_pk_bf16_f32 v57, v53, v55
	v_cvt_pk_bf16_f32 v143, v54, v56
	v_lshrrev_b32_e32 v59, 16, v57
	v_lshrrev_b32_e32 v60, 16, v143
	global_store_short v5, v57, s[24:25] offset:480
	global_store_short v5, v143, s[26:27] offset:480
	global_store_short v5, v59, s[24:25] offset:496
	global_store_short v5, v60, s[26:27] offset:496
	global_store_dwordx4 v10, v[128:131], s[28:29]
	global_store_dwordx4 v10, v[132:135], s[28:29] offset:512
	global_store_dwordx4 v10, v[136:139], s[28:29] offset:1024
	global_store_dwordx4 v10, v[140:143], s[28:29] offset:1536
	s_cmp_lg_u32 s8, 0
	s_cbranch_scc1 .Lgp_noge
	v_mul_f32_e32 v33, 0x3fb8aa3b, v61
	v_exp_f32_e32 v33, v33
	s_nop 0
	global_store_dword v9, v33, s[30:31]
